# attention loops: version the main loop on mref==0 so the two -mref broadcast MFMAs per tile are skipped while no rescale has happened (bit-identical scores); persistent K/V addresses; fewer lgkmcnt wa
# speedup vs baseline: 1.0281x; 1.0281x over previous
; DI int crow(int i, int h) { return (i & 3) + 8 * (i >> 2) + 4 * h; }
; DI int swap23(int r) { return (r & 0x13) | ((r & 4) << 1) | ((r & 8) >> 1); }
;   template <int PAR>
;   DI void step(int t, f32x16 (&cur)[2], f32x16 (&nxt)[2]) {
;     ...
;     float mx = fmaxf(cur[0][0], cur[1][0]);
; #pragma unroll
;     for (int i = 1; i < 16; ++i) mx = fmaxf(fmaxf(cur[0][i], cur[1][i]), mx);
;     if (__builtin_amdgcn_ballot_w64(mx > ATT_THR) != 0ull) {
; template <int DQK>
; DI void attn_item(const u16* __restrict__ Qb, int qpitch, const u16* __restrict__ Kb, int kpitch, const u16* __restrict__ KPEb,
;                   const u16* __restrict__ Vt, float* __restrict__ ssq, int rowq0, int rowk0, int nt, char* smem, int tid, bool dry) {
;     ...
;   f32x16 sa[2], sb[2];
;   c.gload_k(0); c.gload_v(0);
;   __syncthreads();
;   c.sstore_k(0); c.sstore_v(0);
;   if (nt > 1) c.gload_k(1);
;   __syncthreads();
;   c.qk(0, sa);
; #pragma unroll
;   for (int i = 0; i < 16; ++i) {
;     sa[0][i] = -1e30f;
;     if (swap23(crow(i, h)) < 16) sa[1][i] = -1e30f;
;   }
;   int t = 0;
;   for (; t + 1 < nt; t += 2) {
;     c.template step<0>(t, sa, sb);
;     c.template step<1>(t + 1, sb, sa);
;   }
;   if (t < nt) c.template step<0>(t, sa, sb);
.Lg_entry:
	v_mov_b32_e32 v169, 0
	v_mov_b32_e32 v170, 0
	v_mov_b32_e32 v171, 0
	v_mov_b32_e32 v182, 0
	v_mov_b32_e32 v183, 0
	s_sub_i32 s0, s46, 64
	s_ashr_i32 s1, s0, 31
	s_lshl_b64 s[0:1], s[0:1], 8
	s_add_u32 s0, s26, s0
	s_addc_u32 s1, s27, s1
	v_lshl_add_u64 v[214:215], v[184:185], 1, s[0:1]
	v_lshl_add_u64 v[216:217], v[186:187], 1, s[0:1]
	s_mov_b32 s20, 0x4000
	s_mov_b32 s21, 0
	v_max3_f32 v96, v48, v32, v49
	v_max3_f32 v97, v33, v50, v34
	v_max3_f32 v96, v51, v35, v96
	v_max3_f32 v97, v52, v36, v97
	v_max3_f32 v96, v53, v37, v96
	v_max3_f32 v97, v54, v38, v97
	v_max3_f32 v96, v55, v39, v96
	v_max3_f32 v97, v56, v40, v97
	v_max3_f32 v96, v57, v41, v96
	v_max3_f32 v97, v58, v42, v97
	v_max3_f32 v96, v59, v43, v96
	v_max3_f32 v97, v60, v44, v97
	v_max3_f32 v96, v61, v45, v96
	v_max3_f32 v97, v62, v46, v97
	v_max3_f32 v96, v63, v47, v96
	v_max_f32_e32 v96, v96, v97
	v_and_b32_e32 v98, 0x7fff, v168
	v_cmp_ne_u32_e32 vcc, 0, v98
	s_cbranch_vccnz .LBB0_238

; #define MFMA(a, b, c) __builtin_amdgcn_mfma_f32_32x32x16_bf16((a), (b), (c), 0, 0, 0)
; DI unsigned pack2(float a, float b) { f32x2v f = {a, b}; bf16x2v v = __builtin_convertvector(f, bf16x2v); return __builtin_bit_cast(unsigned, v); }
; DI float xhalf(float v) { return __shfl_xor(v, 32); }
;   template <int PAR>
;   DI void step(int t, f32x16 (&cur)[2], f32x16 (&nxt)[2]) {
;     if (t + 1 < nt) sstore_k(PAR ^ 1);
;     if (t > 0) sstore_v(PAR);
;     __syncthreads();
;     if (t + 1 < nt) qk(PAR ^ 1, nxt);
;     float mx = fmaxf(cur[0][0], cur[1][0]);
; #pragma unroll
;     for (int i = 1; i < 16; ++i) mx = fmaxf(fmaxf(cur[0][i], cur[1][i]), mx);
;     if (__builtin_amdgcn_ballot_w64(mx > ATT_THR) != 0ull) {
;       asm volatile("" ::: "memory");
;       mx = fmaxf(mx, xhalf(mx));
;       const float want = mref + fmaxf(mx, 0.f);
;       const float mn = __uint_as_float(pack2(want, 0.f) << 16);
;       const float d = mn - mref;
;       const float alpha = __builtin_amdgcn_exp2f(-d);
;       mref = mn;
;       l *= alpha;
; #pragma unroll
;       for (int a = 0; a < 2; ++a)
; #pragma unroll
;         for (int i = 0; i < 16; ++i) { o[a][i] *= alpha; cur[a][i] -= d; nxt[a][i] -= d; }
;       u32x4 q4 = {h == 0 ? (pack2(-mn, 0.f) & 0xffffu) : 0u, 0u, 0u, 0u};
;       qm = __builtin_bit_cast(bf16x8, q4);
;     }
;     float psum = 0.f;
; #pragma unroll
;     for (int kb2 = 0; kb2 < 2; ++kb2)
; #pragma unroll
;       for (int i = 0; i < 16; ++i) { const float pv = __builtin_amdgcn_exp2f(cur[kb2][i]); cur[kb2][i] = pv; psum += pv; }
;     l += psum;
;     if (t + 2 < nt) gload_k(t + 2);
;     if (t + 1 < nt) gload_v(t + 1);
;     const u16* vb = sV + PAR * VBUF + r * GP + h * 8;
; #pragma unroll
;     for (int kb2 = 0; kb2 < 2; ++kb2)
; #pragma unroll
;       for (int s2 = 0; s2 < 2; ++s2) {
;         u32x4 pk = {pack2(cur[kb2][8 * s2], cur[kb2][8 * s2 + 1]), pack2(cur[kb2][8 * s2 + 2], cur[kb2][8 * s2 + 3]),
;                     pack2(cur[kb2][8 * s2 + 4], cur[kb2][8 * s2 + 5]), pack2(cur[kb2][8 * s2 + 6], cur[kb2][8 * s2 + 7])};
;         const bf16x8 pf = __builtin_bit_cast(bf16x8, pk);
; #pragma unroll
;         for (int db = 0; db < 2; ++db) {
;           const bf16x8 a = *(const bf16x8*)(vb + db * 32 * GP + kb2 * 32 + s2 * 16);
;           o[db] = MFMA(a, pf, o[db]);
;         }
;       }
;   }
.Lgf_rareA_ret:
	s_add_i32 s0, s45, -1
	s_cmp_ge_u32 s0, s19
	s_cselect_b64 s[14:15], -1, 0
	s_cbranch_scc1 .Lgf_skipKA
	global_load_dwordx4 v[152:155], v[214:215], off
	global_load_dwordx4 v[156:159], v[216:217], off
	v_lshl_add_u64 v[214:215], v[214:215], 0, s[20:21]
	v_lshl_add_u64 v[216:217], v[216:217], 0, s[20:21]
.Lgf_skipKA:
	global_load_dwordx4 v[160:163], v[130:131], off offset:-128
	global_load_dwordx4 v[164:167], v[180:181], off offset:-128
	v_exp_f32_e32 v48, v48
	v_exp_f32_e32 v49, v49
	v_exp_f32_e32 v50, v50
	v_add_f32_e32 v182, v48, v182
	v_exp_f32_e32 v51, v51
	v_add_f32_e32 v183, v49, v183
	v_exp_f32_e32 v52, v52
	v_add_f32_e32 v182, v50, v182
	v_exp_f32_e32 v53, v53
	v_add_f32_e32 v183, v51, v183
	s_waitcnt lgkmcnt(0)
	s_barrier
	ds_read_b128 v[96:99], v195 offset:9216
	ds_read_b128 v[100:103], v195 offset:13824
	ds_read_b128 v[104:107], v195 offset:9248
	ds_read_b128 v[108:111], v195 offset:13856
	ds_read_b128 v[112:115], v195 offset:9280
	ds_read_b128 v[116:119], v195 offset:13888
	ds_read_b128 v[120:123], v195 offset:9312
	ds_read_b128 v[124:127], v195 offset:13920
	v_exp_f32_e32 v54, v54
	v_add_f32_e32 v182, v52, v182
	v_exp_f32_e32 v55, v55
	v_add_f32_e32 v183, v53, v183
	v_cvt_pk_bf16_f32 v48, v48, v49
	v_add_f32_e32 v182, v54, v182
	s_waitcnt lgkmcnt(6)
	v_mfma_f32_32x32x16_bf16 v[80:95], v[96:99], v[136:139], 0
	ds_read_b128 v[96:99], v197 offset:18432
	v_cvt_pk_bf16_f32 v49, v50, v51
	v_add_f32_e32 v183, v55, v183
	v_cvt_pk_bf16_f32 v50, v52, v53
	v_cvt_pk_bf16_f32 v51, v54, v55
	v_exp_f32_e32 v56, v56
	v_mfma_f32_32x32x16_bf16 v[64:79], v[100:103], v[136:139], 0
	ds_read_b128 v[100:103], v197 offset:23040
	v_exp_f32_e32 v57, v57
	v_exp_f32_e32 v58, v58
	v_add_f32_e32 v182, v56, v182
	v_exp_f32_e32 v59, v59
	v_add_f32_e32 v183, v57, v183
	s_waitcnt lgkmcnt(6)
	v_mfma_f32_32x32x16_bf16 v[80:95], v[104:107], v[140:143], v[80:95]
	ds_read_b128 v[104:107], v197 offset:18464
	v_exp_f32_e32 v60, v60
	v_add_f32_e32 v182, v58, v182
	v_exp_f32_e32 v61, v61
	v_add_f32_e32 v183, v59, v183
	v_exp_f32_e32 v62, v62
	v_mfma_f32_32x32x16_bf16 v[64:79], v[108:111], v[140:143], v[64:79]
	ds_read_b128 v[108:111], v197 offset:23072
	v_add_f32_e32 v182, v60, v182
	v_exp_f32_e32 v63, v63
	v_add_f32_e32 v183, v61, v183
	v_cvt_pk_bf16_f32 v56, v56, v57
	v_add_f32_e32 v182, v62, v182
	s_waitcnt lgkmcnt(6)
	v_mfma_f32_32x32x16_bf16 v[80:95], v[112:115], v[144:147], v[80:95]
	ds_read_b128 v[112:115], v197 offset:18496
	v_cvt_pk_bf16_f32 v57, v58, v59
	v_add_f32_e32 v183, v63, v183
	v_cvt_pk_bf16_f32 v58, v60, v61
	v_cvt_pk_bf16_f32 v59, v62, v63
	v_exp_f32_e32 v32, v32
	v_mfma_f32_32x32x16_bf16 v[64:79], v[116:119], v[144:147], v[64:79]
	ds_read_b128 v[116:119], v197 offset:23104
	v_exp_f32_e32 v33, v33
	v_exp_f32_e32 v34, v34
	v_add_f32_e32 v182, v32, v182
	v_exp_f32_e32 v35, v35
	v_add_f32_e32 v183, v33, v183
	s_waitcnt lgkmcnt(6)
	v_mfma_f32_32x32x16_bf16 v[80:95], v[120:123], v[148:151], v[80:95]
	ds_read_b128 v[120:123], v197 offset:18528
	v_exp_f32_e32 v36, v36
	v_add_f32_e32 v182, v34, v182
	v_exp_f32_e32 v37, v37
	v_add_f32_e32 v183, v35, v183
	v_exp_f32_e32 v38, v38
	v_mfma_f32_32x32x16_bf16 v[64:79], v[124:127], v[148:151], v[64:79]
	ds_read_b128 v[124:127], v197 offset:23136
	v_add_f32_e32 v182, v36, v182
	v_exp_f32_e32 v39, v39
	v_add_f32_e32 v183, v37, v183
	v_cvt_pk_bf16_f32 v32, v32, v33
	v_add_f32_e32 v182, v38, v182
	s_waitcnt lgkmcnt(4)
	v_mfma_f32_32x32x16_bf16 v[16:31], v[96:99], v[48:51], v[16:31]
	v_cvt_pk_bf16_f32 v33, v34, v35
	v_add_f32_e32 v183, v39, v183
	v_cvt_pk_bf16_f32 v34, v36, v37
	v_cvt_pk_bf16_f32 v35, v38, v39
	v_exp_f32_e32 v40, v40
	v_mfma_f32_32x32x16_bf16 v[0:15], v[100:103], v[48:51], v[0:15]
	v_exp_f32_e32 v41, v41
	v_exp_f32_e32 v42, v42
	v_add_f32_e32 v182, v40, v182
	v_exp_f32_e32 v43, v43
	v_add_f32_e32 v183, v41, v183
	v_mfma_f32_32x32x16_bf16 v[16:31], v[104:107], v[56:59], v[16:31]
	v_exp_f32_e32 v44, v44
	v_add_f32_e32 v182, v42, v182
	v_exp_f32_e32 v45, v45
	v_add_f32_e32 v183, v43, v183
	v_exp_f32_e32 v46, v46
	v_mfma_f32_32x32x16_bf16 v[0:15], v[108:111], v[56:59], v[0:15]
	v_add_f32_e32 v182, v44, v182
	v_exp_f32_e32 v47, v47
	v_add_f32_e32 v183, v45, v183
	v_cvt_pk_bf16_f32 v40, v40, v41
	v_add_f32_e32 v182, v46, v182
	s_waitcnt lgkmcnt(0)
	v_mfma_f32_32x32x16_bf16 v[16:31], v[112:115], v[32:35], v[16:31]
	v_cvt_pk_bf16_f32 v41, v42, v43
	v_add_f32_e32 v183, v47, v183
	v_cvt_pk_bf16_f32 v42, v44, v45
	v_cvt_pk_bf16_f32 v43, v46, v47
	v_max3_f32 v96, v80, v64, v81
	v_mfma_f32_32x32x16_bf16 v[0:15], v[116:119], v[32:35], v[0:15]
	v_max3_f32 v97, v65, v82, v66
	v_max3_f32 v96, v83, v67, v96
	v_max3_f32 v97, v84, v68, v97
	v_max3_f32 v96, v85, v69, v96
	v_max3_f32 v97, v86, v70, v97
	v_mfma_f32_32x32x16_bf16 v[16:31], v[120:123], v[40:43], v[16:31]
	v_max3_f32 v96, v87, v71, v96
	v_max3_f32 v97, v88, v72, v97
	v_max3_f32 v96, v89, v73, v96
	v_max3_f32 v97, v90, v74, v97
	v_max3_f32 v96, v91, v75, v96
	v_mfma_f32_32x32x16_bf16 v[0:15], v[124:127], v[40:43], v[0:15]
	v_max3_f32 v97, v92, v76, v97
	v_max3_f32 v96, v93, v77, v96
	v_max3_f32 v97, v94, v78, v97
	v_max3_f32 v96, v95, v79, v96
	v_max_f32_e32 v96, v96, v97
	s_waitcnt vmcnt(0)
	ds_write_b128 v248, v[152:155]
	ds_write_b128 v249, v[156:159]
	ds_write_b128 v194, v[160:163] offset:27648
	ds_write_b128 v196, v[164:167] offset:27648
	v_cmp_lt_f32_e32 vcc, s65, v96
	s_cbranch_vccnz .Lgf_rareB
.Lgf_rareB_ret:
	s_cmp_ge_u32 s45, s19
	s_cbranch_scc1 .Lgf_skipKB
	global_load_dwordx4 v[152:155], v[214:215], off
	global_load_dwordx4 v[156:159], v[216:217], off
	v_lshl_add_u64 v[214:215], v[214:215], 0, s[20:21]
	v_lshl_add_u64 v[216:217], v[216:217], 0, s[20:21]

; #define MFMA(a, b, c) __builtin_amdgcn_mfma_f32_32x32x16_bf16((a), (b), (c), 0, 0, 0)
; DI unsigned pack2(float a, float b) { f32x2v f = {a, b}; bf16x2v v = __builtin_convertvector(f, bf16x2v); return __builtin_bit_cast(unsigned, v); }
; DI float xhalf(float v) { return __shfl_xor(v, 32); }
;   template <int PAR>
;   DI void step(int t, f32x16 (&cur)[2], f32x16 (&nxt)[2]) {
;     if (t + 1 < nt) sstore_k(PAR ^ 1);
;     if (t > 0) sstore_v(PAR);
;     __syncthreads();
;     if (t + 1 < nt) qk(PAR ^ 1, nxt);
;     float mx = fmaxf(cur[0][0], cur[1][0]);
; #pragma unroll
;     for (int i = 1; i < 16; ++i) mx = fmaxf(fmaxf(cur[0][i], cur[1][i]), mx);
;     if (__builtin_amdgcn_ballot_w64(mx > ATT_THR) != 0ull) {
;       asm volatile("" ::: "memory");
;       mx = fmaxf(mx, xhalf(mx));
;       const float want = mref + fmaxf(mx, 0.f);
;       const float mn = __uint_as_float(pack2(want, 0.f) << 16);
;       const float d = mn - mref;
;       const float alpha = __builtin_amdgcn_exp2f(-d);
;       mref = mn;
;       l *= alpha;
; #pragma unroll
;       for (int a = 0; a < 2; ++a)
; #pragma unroll
;         for (int i = 0; i < 16; ++i) { o[a][i] *= alpha; cur[a][i] -= d; nxt[a][i] -= d; }
;       u32x4 q4 = {h == 0 ? (pack2(-mn, 0.f) & 0xffffu) : 0u, 0u, 0u, 0u};
;       qm = __builtin_bit_cast(bf16x8, q4);
;     }
;     float psum = 0.f;
; #pragma unroll
;     for (int kb2 = 0; kb2 < 2; ++kb2)
; #pragma unroll
;       for (int i = 0; i < 16; ++i) { const float pv = __builtin_amdgcn_exp2f(cur[kb2][i]); cur[kb2][i] = pv; psum += pv; }
;     l += psum;
;     if (t + 2 < nt) gload_k(t + 2);
;     if (t + 1 < nt) gload_v(t + 1);
;     const u16* vb = sV + PAR * VBUF + r * GP + h * 8;
; #pragma unroll
;     for (int kb2 = 0; kb2 < 2; ++kb2)
; #pragma unroll
;       for (int s2 = 0; s2 < 2; ++s2) {
;         u32x4 pk = {pack2(cur[kb2][8 * s2], cur[kb2][8 * s2 + 1]), pack2(cur[kb2][8 * s2 + 2], cur[kb2][8 * s2 + 3]),
;                     pack2(cur[kb2][8 * s2 + 4], cur[kb2][8 * s2 + 5]), pack2(cur[kb2][8 * s2 + 6], cur[kb2][8 * s2 + 7])};
;         const bf16x8 pf = __builtin_bit_cast(bf16x8, pk);
; #pragma unroll
;         for (int db = 0; db < 2; ++db) {
;           const bf16x8 a = *(const bf16x8*)(vb + db * 32 * GP + kb2 * 32 + s2 * 16);
;           o[db] = MFMA(a, pf, o[db]);
;         }
;       }
;   }
.Lgf_skipVB:
	v_exp_f32_e32 v80, v80
	v_exp_f32_e32 v81, v81
	v_exp_f32_e32 v82, v82
	v_add_f32_e32 v182, v80, v182
	v_exp_f32_e32 v83, v83
	v_add_f32_e32 v183, v81, v183
	v_exp_f32_e32 v84, v84
	v_add_f32_e32 v182, v82, v182
	v_exp_f32_e32 v85, v85
	v_add_f32_e32 v183, v83, v183
	s_waitcnt lgkmcnt(0)
	s_barrier
	ds_read_b128 v[96:99], v195
	ds_read_b128 v[100:103], v195 offset:4608
	ds_read_b128 v[104:107], v195 offset:32
	ds_read_b128 v[108:111], v195 offset:4640
	ds_read_b128 v[112:115], v195 offset:64
	ds_read_b128 v[116:119], v195 offset:4672
	ds_read_b128 v[120:123], v195 offset:96
	ds_read_b128 v[124:127], v195 offset:4704
	v_exp_f32_e32 v86, v86
	v_add_f32_e32 v182, v84, v182
	v_exp_f32_e32 v87, v87
	v_add_f32_e32 v183, v85, v183
	v_cvt_pk_bf16_f32 v80, v80, v81
	v_add_f32_e32 v182, v86, v182
	s_waitcnt lgkmcnt(6)
	v_mfma_f32_32x32x16_bf16 v[48:63], v[96:99], v[136:139], 0
	ds_read_b128 v[96:99], v197 offset:27648
	v_cvt_pk_bf16_f32 v81, v82, v83
	v_add_f32_e32 v183, v87, v183
	v_cvt_pk_bf16_f32 v82, v84, v85
	v_cvt_pk_bf16_f32 v83, v86, v87
	v_exp_f32_e32 v88, v88
	v_mfma_f32_32x32x16_bf16 v[32:47], v[100:103], v[136:139], 0
	ds_read_b128 v[100:103], v197 offset:32256
	v_exp_f32_e32 v89, v89
	v_exp_f32_e32 v90, v90
	v_add_f32_e32 v182, v88, v182
	v_exp_f32_e32 v91, v91
	v_add_f32_e32 v183, v89, v183
	s_waitcnt lgkmcnt(6)
	v_mfma_f32_32x32x16_bf16 v[48:63], v[104:107], v[140:143], v[48:63]
	ds_read_b128 v[104:107], v197 offset:27680
	v_exp_f32_e32 v92, v92
	v_add_f32_e32 v182, v90, v182
	v_exp_f32_e32 v93, v93
	v_add_f32_e32 v183, v91, v183
	v_exp_f32_e32 v94, v94
	v_mfma_f32_32x32x16_bf16 v[32:47], v[108:111], v[140:143], v[32:47]
	ds_read_b128 v[108:111], v197 offset:32288
	v_add_f32_e32 v182, v92, v182
	v_exp_f32_e32 v95, v95
	v_add_f32_e32 v183, v93, v183
	v_cvt_pk_bf16_f32 v88, v88, v89
	v_add_f32_e32 v182, v94, v182
	s_waitcnt lgkmcnt(6)
	v_mfma_f32_32x32x16_bf16 v[48:63], v[112:115], v[144:147], v[48:63]
	ds_read_b128 v[112:115], v197 offset:27712
	v_cvt_pk_bf16_f32 v89, v90, v91
	v_add_f32_e32 v183, v95, v183
	v_cvt_pk_bf16_f32 v90, v92, v93
	v_cvt_pk_bf16_f32 v91, v94, v95
	v_exp_f32_e32 v64, v64
	v_mfma_f32_32x32x16_bf16 v[32:47], v[116:119], v[144:147], v[32:47]
	ds_read_b128 v[116:119], v197 offset:32320
	v_exp_f32_e32 v65, v65
	v_exp_f32_e32 v66, v66
	v_add_f32_e32 v182, v64, v182
	v_exp_f32_e32 v67, v67
	v_add_f32_e32 v183, v65, v183
	s_waitcnt lgkmcnt(6)
	v_mfma_f32_32x32x16_bf16 v[48:63], v[120:123], v[148:151], v[48:63]
	ds_read_b128 v[120:123], v197 offset:27744
	v_exp_f32_e32 v68, v68
	v_add_f32_e32 v182, v66, v182
	v_exp_f32_e32 v69, v69
	v_add_f32_e32 v183, v67, v183
	v_exp_f32_e32 v70, v70
	v_mfma_f32_32x32x16_bf16 v[32:47], v[124:127], v[148:151], v[32:47]
	ds_read_b128 v[124:127], v197 offset:32352
	v_add_f32_e32 v182, v68, v182
	v_exp_f32_e32 v71, v71
	v_add_f32_e32 v183, v69, v183
	v_cvt_pk_bf16_f32 v64, v64, v65
	v_add_f32_e32 v182, v70, v182
	s_waitcnt lgkmcnt(4)
	v_mfma_f32_32x32x16_bf16 v[16:31], v[96:99], v[80:83], v[16:31]
	v_cvt_pk_bf16_f32 v65, v66, v67
	v_add_f32_e32 v183, v71, v183
	v_cvt_pk_bf16_f32 v66, v68, v69
	v_cvt_pk_bf16_f32 v67, v70, v71
	v_exp_f32_e32 v72, v72
	v_mfma_f32_32x32x16_bf16 v[0:15], v[100:103], v[80:83], v[0:15]
	v_exp_f32_e32 v73, v73
	v_exp_f32_e32 v74, v74
	v_add_f32_e32 v182, v72, v182
	v_exp_f32_e32 v75, v75
	v_add_f32_e32 v183, v73, v183
	v_mfma_f32_32x32x16_bf16 v[16:31], v[104:107], v[88:91], v[16:31]
	v_exp_f32_e32 v76, v76
	v_add_f32_e32 v182, v74, v182
	v_exp_f32_e32 v77, v77
	v_add_f32_e32 v183, v75, v183
	v_exp_f32_e32 v78, v78
	v_mfma_f32_32x32x16_bf16 v[0:15], v[108:111], v[88:91], v[0:15]
	v_add_f32_e32 v182, v76, v182
	v_exp_f32_e32 v79, v79
	v_add_f32_e32 v183, v77, v183
	v_cvt_pk_bf16_f32 v72, v72, v73
	v_add_f32_e32 v182, v78, v182
	s_waitcnt lgkmcnt(0)
	v_mfma_f32_32x32x16_bf16 v[16:31], v[112:115], v[64:67], v[16:31]
	v_cvt_pk_bf16_f32 v73, v74, v75
	v_add_f32_e32 v183, v79, v183
	v_cvt_pk_bf16_f32 v74, v76, v77
	v_cvt_pk_bf16_f32 v75, v78, v79
	v_max3_f32 v96, v48, v32, v49
	v_mfma_f32_32x32x16_bf16 v[0:15], v[116:119], v[64:67], v[0:15]
	v_max3_f32 v97, v33, v50, v34
	v_max3_f32 v96, v51, v35, v96
	v_max3_f32 v97, v52, v36, v97
	v_max3_f32 v96, v53, v37, v96
	v_max3_f32 v97, v54, v38, v97
	v_mfma_f32_32x32x16_bf16 v[16:31], v[120:123], v[72:75], v[16:31]
	v_max3_f32 v96, v55, v39, v96
	v_max3_f32 v97, v56, v40, v97
	v_max3_f32 v96, v57, v41, v96
	v_max3_f32 v97, v58, v42, v97
	v_max3_f32 v96, v59, v43, v96
	v_mfma_f32_32x32x16_bf16 v[0:15], v[124:127], v[72:75], v[0:15]
	v_max3_f32 v97, v60, v44, v97
	v_max3_f32 v96, v61, v45, v96
	v_max3_f32 v97, v62, v46, v97
	v_max3_f32 v96, v63, v47, v96
	v_max_f32_e32 v96, v96, v97
	v_lshl_add_u64 v[130:131], v[130:131], 0, s[84:85]
	v_lshl_add_u64 v[180:181], v[180:181], 0, s[84:85]
	s_mov_b32 s0, s45
	s_add_i32 s45, s45, 2
	s_cmp_lt_u32 s0, s19
	s_cbranch_scc1 .Lgf_top
	s_branch .Lg_fold

; #define MFMA(a, b, c) __builtin_amdgcn_mfma_f32_32x32x16_bf16((a), (b), (c), 0, 0, 0)
; DI unsigned pack2(float a, float b) { f32x2v f = {a, b}; bf16x2v v = __builtin_convertvector(f, bf16x2v); return __builtin_bit_cast(unsigned, v); }
; DI float xhalf(float v) { return __shfl_xor(v, 32); }
;   template <int PAR>
;   DI void step(int t, f32x16 (&cur)[2], f32x16 (&nxt)[2]) {
;     if (t + 1 < nt) sstore_k(PAR ^ 1);
;     if (t > 0) sstore_v(PAR);
;     __syncthreads();
;     if (t + 1 < nt) qk(PAR ^ 1, nxt);
;     float mx = fmaxf(cur[0][0], cur[1][0]);
; #pragma unroll
;     for (int i = 1; i < 16; ++i) mx = fmaxf(fmaxf(cur[0][i], cur[1][i]), mx);
;     if (__builtin_amdgcn_ballot_w64(mx > ATT_THR) != 0ull) {
;       asm volatile("" ::: "memory");
;       mx = fmaxf(mx, xhalf(mx));
;       const float want = mref + fmaxf(mx, 0.f);
;       const float mn = __uint_as_float(pack2(want, 0.f) << 16);
;       const float d = mn - mref;
;       const float alpha = __builtin_amdgcn_exp2f(-d);
;       mref = mn;
;       l *= alpha;
; #pragma unroll
;       for (int a = 0; a < 2; ++a)
; #pragma unroll
;         for (int i = 0; i < 16; ++i) { o[a][i] *= alpha; cur[a][i] -= d; nxt[a][i] -= d; }
;       u32x4 q4 = {h == 0 ? (pack2(-mn, 0.f) & 0xffffu) : 0u, 0u, 0u, 0u};
;       qm = __builtin_bit_cast(bf16x8, q4);
;     }
;     float psum = 0.f;
; #pragma unroll
;     for (int kb2 = 0; kb2 < 2; ++kb2)
; #pragma unroll
;       for (int i = 0; i < 16; ++i) { const float pv = __builtin_amdgcn_exp2f(cur[kb2][i]); cur[kb2][i] = pv; psum += pv; }
;     l += psum;
;     if (t + 2 < nt) gload_k(t + 2);
;     if (t + 1 < nt) gload_v(t + 1);
;     const u16* vb = sV + PAR * VBUF + r * GP + h * 8;
; #pragma unroll
;     for (int kb2 = 0; kb2 < 2; ++kb2)
; #pragma unroll
;       for (int s2 = 0; s2 < 2; ++s2) {
;         u32x4 pk = {pack2(cur[kb2][8 * s2], cur[kb2][8 * s2 + 1]), pack2(cur[kb2][8 * s2 + 2], cur[kb2][8 * s2 + 3]),
;                     pack2(cur[kb2][8 * s2 + 4], cur[kb2][8 * s2 + 5]), pack2(cur[kb2][8 * s2 + 6], cur[kb2][8 * s2 + 7])};
;         const bf16x8 pf = __builtin_bit_cast(bf16x8, pk);
; #pragma unroll
;         for (int db = 0; db < 2; ++db) {
;           const bf16x8 a = *(const bf16x8*)(vb + db * 32 * GP + kb2 * 32 + s2 * 16);
;           o[db] = MFMA(a, pf, o[db]);
;         }
;       }
;   }
.Lg_skipKA:
	global_load_dwordx4 v[160:163], v[130:131], off offset:-128
	global_load_dwordx4 v[164:167], v[180:181], off offset:-128
	v_exp_f32_e32 v48, v48
	v_exp_f32_e32 v49, v49
	v_exp_f32_e32 v50, v50
	v_add_f32_e32 v182, v48, v182
	v_exp_f32_e32 v51, v51
	v_add_f32_e32 v183, v49, v183
	v_exp_f32_e32 v52, v52
	v_add_f32_e32 v182, v50, v182
	v_exp_f32_e32 v53, v53
	v_add_f32_e32 v183, v51, v183
	s_waitcnt lgkmcnt(0)
	s_barrier
	ds_read_b128 v[96:99], v195 offset:9216
	ds_read_b128 v[100:103], v195 offset:13824
	ds_read_b128 v[104:107], v195 offset:9248
	ds_read_b128 v[108:111], v195 offset:13856
	ds_read_b128 v[112:115], v195 offset:9280
	ds_read_b128 v[116:119], v195 offset:13888
	ds_read_b128 v[120:123], v195 offset:9312
	ds_read_b128 v[124:127], v195 offset:13920
	v_exp_f32_e32 v54, v54
	v_add_f32_e32 v182, v52, v182
	v_exp_f32_e32 v55, v55
	v_add_f32_e32 v183, v53, v183
	v_cvt_pk_bf16_f32 v48, v48, v49
	v_add_f32_e32 v182, v54, v182
	s_waitcnt lgkmcnt(6)
	v_mfma_f32_32x32x16_bf16 v[80:95], v[96:99], v[136:139], 0
	ds_read_b128 v[96:99], v197 offset:18432
	v_cvt_pk_bf16_f32 v49, v50, v51
	v_add_f32_e32 v183, v55, v183
	v_cvt_pk_bf16_f32 v50, v52, v53
	v_cvt_pk_bf16_f32 v51, v54, v55
	v_exp_f32_e32 v56, v56
	v_mfma_f32_32x32x16_bf16 v[64:79], v[100:103], v[136:139], 0
	ds_read_b128 v[100:103], v197 offset:23040
	v_exp_f32_e32 v57, v57
	v_exp_f32_e32 v58, v58
	v_add_f32_e32 v182, v56, v182
	v_exp_f32_e32 v59, v59
	v_add_f32_e32 v183, v57, v183
	s_waitcnt lgkmcnt(6)
	v_mfma_f32_32x32x16_bf16 v[80:95], v[104:107], v[140:143], v[80:95]
	ds_read_b128 v[104:107], v197 offset:18464
	v_exp_f32_e32 v60, v60
	v_add_f32_e32 v182, v58, v182
	v_exp_f32_e32 v61, v61
	v_add_f32_e32 v183, v59, v183
	v_exp_f32_e32 v62, v62
	v_mfma_f32_32x32x16_bf16 v[64:79], v[108:111], v[140:143], v[64:79]
	ds_read_b128 v[108:111], v197 offset:23072
	v_add_f32_e32 v182, v60, v182
	v_exp_f32_e32 v63, v63
	v_add_f32_e32 v183, v61, v183
	v_cvt_pk_bf16_f32 v56, v56, v57
	v_add_f32_e32 v182, v62, v182
	s_waitcnt lgkmcnt(6)
	v_mfma_f32_32x32x16_bf16 v[80:95], v[112:115], v[144:147], v[80:95]
	ds_read_b128 v[112:115], v197 offset:18496
	v_cvt_pk_bf16_f32 v57, v58, v59
	v_add_f32_e32 v183, v63, v183
	v_cvt_pk_bf16_f32 v58, v60, v61
	v_cvt_pk_bf16_f32 v59, v62, v63
	v_exp_f32_e32 v32, v32
	v_mfma_f32_32x32x16_bf16 v[64:79], v[116:119], v[144:147], v[64:79]
	ds_read_b128 v[116:119], v197 offset:23104
	v_exp_f32_e32 v33, v33
	v_exp_f32_e32 v34, v34
	v_add_f32_e32 v182, v32, v182
	v_exp_f32_e32 v35, v35
	v_add_f32_e32 v183, v33, v183
	s_waitcnt lgkmcnt(6)
	v_mfma_f32_32x32x16_bf16 v[80:95], v[120:123], v[148:151], v[80:95]
	ds_read_b128 v[120:123], v197 offset:18528
	v_exp_f32_e32 v36, v36
	v_add_f32_e32 v182, v34, v182
	v_exp_f32_e32 v37, v37
	v_add_f32_e32 v183, v35, v183
	v_exp_f32_e32 v38, v38
	v_mfma_f32_32x32x16_bf16 v[64:79], v[124:127], v[148:151], v[64:79]
	ds_read_b128 v[124:127], v197 offset:23136
	v_add_f32_e32 v182, v36, v182
	v_exp_f32_e32 v39, v39
	v_add_f32_e32 v183, v37, v183
	v_cvt_pk_bf16_f32 v32, v32, v33
	v_add_f32_e32 v182, v38, v182
	v_mfma_f32_32x32x16_bf16 v[80:95], v[132:135], v[168:171], v[80:95]
	v_cvt_pk_bf16_f32 v33, v34, v35
	v_add_f32_e32 v183, v39, v183
	v_cvt_pk_bf16_f32 v34, v36, v37
	v_cvt_pk_bf16_f32 v35, v38, v39
	v_mfma_f32_32x32x16_bf16 v[64:79], v[132:135], v[168:171], v[64:79]
	v_exp_f32_e32 v40, v40
	v_exp_f32_e32 v41, v41
	v_exp_f32_e32 v42, v42
	v_add_f32_e32 v182, v40, v182
	s_waitcnt lgkmcnt(4)
	v_mfma_f32_32x32x16_bf16 v[16:31], v[96:99], v[48:51], v[16:31]
	v_exp_f32_e32 v43, v43
	v_add_f32_e32 v183, v41, v183
	v_exp_f32_e32 v44, v44
	v_add_f32_e32 v182, v42, v182
	v_mfma_f32_32x32x16_bf16 v[0:15], v[100:103], v[48:51], v[0:15]
	v_exp_f32_e32 v45, v45
	v_add_f32_e32 v183, v43, v183
	v_exp_f32_e32 v46, v46
	v_add_f32_e32 v182, v44, v182
	v_mfma_f32_32x32x16_bf16 v[16:31], v[104:107], v[56:59], v[16:31]
	v_exp_f32_e32 v47, v47
	v_add_f32_e32 v183, v45, v183
	v_cvt_pk_bf16_f32 v40, v40, v41
	v_add_f32_e32 v182, v46, v182
	v_mfma_f32_32x32x16_bf16 v[0:15], v[108:111], v[56:59], v[0:15]
	v_cvt_pk_bf16_f32 v41, v42, v43
	v_add_f32_e32 v183, v47, v183
	v_cvt_pk_bf16_f32 v42, v44, v45
	v_cvt_pk_bf16_f32 v43, v46, v47
	s_waitcnt lgkmcnt(0)
	v_mfma_f32_32x32x16_bf16 v[16:31], v[112:115], v[32:35], v[16:31]
	v_max3_f32 v96, v80, v64, v81
	v_max3_f32 v97, v65, v82, v66
	v_max3_f32 v96, v83, v67, v96
	v_max3_f32 v97, v84, v68, v97
	v_mfma_f32_32x32x16_bf16 v[0:15], v[116:119], v[32:35], v[0:15]
	v_max3_f32 v96, v85, v69, v96
	v_max3_f32 v97, v86, v70, v97
	v_max3_f32 v96, v87, v71, v96
	v_max3_f32 v97, v88, v72, v97
	v_mfma_f32_32x32x16_bf16 v[16:31], v[120:123], v[40:43], v[16:31]
	v_max3_f32 v96, v89, v73, v96
	v_max3_f32 v97, v90, v74, v97
	v_max3_f32 v96, v91, v75, v96
	v_max3_f32 v97, v92, v76, v97
	v_mfma_f32_32x32x16_bf16 v[0:15], v[124:127], v[40:43], v[0:15]
	v_max3_f32 v96, v93, v77, v96
	v_max3_f32 v97, v94, v78, v97
	v_max3_f32 v96, v95, v79, v96
	v_max_f32_e32 v96, v96, v97
	s_waitcnt vmcnt(0)
	ds_write_b128 v248, v[152:155]
	ds_write_b128 v249, v[156:159]
	ds_write_b128 v194, v[160:163] offset:27648
	ds_write_b128 v196, v[164:167] offset:27648
	v_cmp_lt_f32_e32 vcc, s65, v96
	s_cbranch_vccnz .Lg_rareB

; #define MFMA(a, b, c) __builtin_amdgcn_mfma_f32_32x32x16_bf16((a), (b), (c), 0, 0, 0)
; DI unsigned pack2(float a, float b) { f32x2v f = {a, b}; bf16x2v v = __builtin_convertvector(f, bf16x2v); return __builtin_bit_cast(unsigned, v); }
; DI float xhalf(float v) { return __shfl_xor(v, 32); }
;   template <int PAR>
;   DI void step(int t, f32x16 (&cur)[2], f32x16 (&nxt)[2]) {
;     if (t + 1 < nt) sstore_k(PAR ^ 1);
;     if (t > 0) sstore_v(PAR);
;     __syncthreads();
;     if (t + 1 < nt) qk(PAR ^ 1, nxt);
;     float mx = fmaxf(cur[0][0], cur[1][0]);
; #pragma unroll
;     for (int i = 1; i < 16; ++i) mx = fmaxf(fmaxf(cur[0][i], cur[1][i]), mx);
;     if (__builtin_amdgcn_ballot_w64(mx > ATT_THR) != 0ull) {
;       asm volatile("" ::: "memory");
;       mx = fmaxf(mx, xhalf(mx));
;       const float want = mref + fmaxf(mx, 0.f);
;       const float mn = __uint_as_float(pack2(want, 0.f) << 16);
;       const float d = mn - mref;
;       const float alpha = __builtin_amdgcn_exp2f(-d);
;       mref = mn;
;       l *= alpha;
; #pragma unroll
;       for (int a = 0; a < 2; ++a)
; #pragma unroll
;         for (int i = 0; i < 16; ++i) { o[a][i] *= alpha; cur[a][i] -= d; nxt[a][i] -= d; }
;       u32x4 q4 = {h == 0 ? (pack2(-mn, 0.f) & 0xffffu) : 0u, 0u, 0u, 0u};
;       qm = __builtin_bit_cast(bf16x8, q4);
;     }
;     float psum = 0.f;
; #pragma unroll
;     for (int kb2 = 0; kb2 < 2; ++kb2)
; #pragma unroll
;       for (int i = 0; i < 16; ++i) { const float pv = __builtin_amdgcn_exp2f(cur[kb2][i]); cur[kb2][i] = pv; psum += pv; }
;     l += psum;
;     if (t + 2 < nt) gload_k(t + 2);
;     if (t + 1 < nt) gload_v(t + 1);
;     const u16* vb = sV + PAR * VBUF + r * GP + h * 8;
; #pragma unroll
;     for (int kb2 = 0; kb2 < 2; ++kb2)
; #pragma unroll
;       for (int s2 = 0; s2 < 2; ++s2) {
;         u32x4 pk = {pack2(cur[kb2][8 * s2], cur[kb2][8 * s2 + 1]), pack2(cur[kb2][8 * s2 + 2], cur[kb2][8 * s2 + 3]),
;                     pack2(cur[kb2][8 * s2 + 4], cur[kb2][8 * s2 + 5]), pack2(cur[kb2][8 * s2 + 6], cur[kb2][8 * s2 + 7])};
;         const bf16x8 pf = __builtin_bit_cast(bf16x8, pk);
; #pragma unroll
;         for (int db = 0; db < 2; ++db) {
;           const bf16x8 a = *(const bf16x8*)(vb + db * 32 * GP + kb2 * 32 + s2 * 16);
;           o[db] = MFMA(a, pf, o[db]);
;         }
;       }
;   }
.Lg_skipVB:
	v_exp_f32_e32 v80, v80
	v_exp_f32_e32 v81, v81
	v_exp_f32_e32 v82, v82
	v_add_f32_e32 v182, v80, v182
	v_exp_f32_e32 v83, v83
	v_add_f32_e32 v183, v81, v183
	v_exp_f32_e32 v84, v84
	v_add_f32_e32 v182, v82, v182
	v_exp_f32_e32 v85, v85
	v_add_f32_e32 v183, v83, v183
	s_waitcnt lgkmcnt(0)
	s_barrier
	ds_read_b128 v[96:99], v195
	ds_read_b128 v[100:103], v195 offset:4608
	ds_read_b128 v[104:107], v195 offset:32
	ds_read_b128 v[108:111], v195 offset:4640
	ds_read_b128 v[112:115], v195 offset:64
	ds_read_b128 v[116:119], v195 offset:4672
	ds_read_b128 v[120:123], v195 offset:96
	ds_read_b128 v[124:127], v195 offset:4704
	v_exp_f32_e32 v86, v86
	v_add_f32_e32 v182, v84, v182
	v_exp_f32_e32 v87, v87
	v_add_f32_e32 v183, v85, v183
	v_cvt_pk_bf16_f32 v80, v80, v81
	v_add_f32_e32 v182, v86, v182
	s_waitcnt lgkmcnt(6)
	v_mfma_f32_32x32x16_bf16 v[48:63], v[96:99], v[136:139], 0
	ds_read_b128 v[96:99], v197 offset:27648
	v_cvt_pk_bf16_f32 v81, v82, v83
	v_add_f32_e32 v183, v87, v183
	v_cvt_pk_bf16_f32 v82, v84, v85
	v_cvt_pk_bf16_f32 v83, v86, v87
	v_exp_f32_e32 v88, v88
	v_mfma_f32_32x32x16_bf16 v[32:47], v[100:103], v[136:139], 0
	ds_read_b128 v[100:103], v197 offset:32256
	v_exp_f32_e32 v89, v89
	v_exp_f32_e32 v90, v90
	v_add_f32_e32 v182, v88, v182
	v_exp_f32_e32 v91, v91
	v_add_f32_e32 v183, v89, v183
	s_waitcnt lgkmcnt(6)
	v_mfma_f32_32x32x16_bf16 v[48:63], v[104:107], v[140:143], v[48:63]
	ds_read_b128 v[104:107], v197 offset:27680
	v_exp_f32_e32 v92, v92
	v_add_f32_e32 v182, v90, v182
	v_exp_f32_e32 v93, v93
	v_add_f32_e32 v183, v91, v183
	v_exp_f32_e32 v94, v94
	v_mfma_f32_32x32x16_bf16 v[32:47], v[108:111], v[140:143], v[32:47]
	ds_read_b128 v[108:111], v197 offset:32288
	v_add_f32_e32 v182, v92, v182
	v_exp_f32_e32 v95, v95
	v_add_f32_e32 v183, v93, v183
	v_cvt_pk_bf16_f32 v88, v88, v89
	v_add_f32_e32 v182, v94, v182
	s_waitcnt lgkmcnt(6)
	v_mfma_f32_32x32x16_bf16 v[48:63], v[112:115], v[144:147], v[48:63]
	ds_read_b128 v[112:115], v197 offset:27712
	v_cvt_pk_bf16_f32 v89, v90, v91
	v_add_f32_e32 v183, v95, v183
	v_cvt_pk_bf16_f32 v90, v92, v93
	v_cvt_pk_bf16_f32 v91, v94, v95
	v_exp_f32_e32 v64, v64
	v_mfma_f32_32x32x16_bf16 v[32:47], v[116:119], v[144:147], v[32:47]
	ds_read_b128 v[116:119], v197 offset:32320
	v_exp_f32_e32 v65, v65
	v_exp_f32_e32 v66, v66
	v_add_f32_e32 v182, v64, v182
	v_exp_f32_e32 v67, v67
	v_add_f32_e32 v183, v65, v183
	s_waitcnt lgkmcnt(6)
	v_mfma_f32_32x32x16_bf16 v[48:63], v[120:123], v[148:151], v[48:63]
	ds_read_b128 v[120:123], v197 offset:27744
	v_exp_f32_e32 v68, v68
	v_add_f32_e32 v182, v66, v182
	v_exp_f32_e32 v69, v69
	v_add_f32_e32 v183, v67, v183
	v_exp_f32_e32 v70, v70
	v_mfma_f32_32x32x16_bf16 v[32:47], v[124:127], v[148:151], v[32:47]
	ds_read_b128 v[124:127], v197 offset:32352
	v_add_f32_e32 v182, v68, v182
	v_exp_f32_e32 v71, v71
	v_add_f32_e32 v183, v69, v183
	v_cvt_pk_bf16_f32 v64, v64, v65
	v_add_f32_e32 v182, v70, v182
	v_mfma_f32_32x32x16_bf16 v[48:63], v[132:135], v[168:171], v[48:63]
	v_cvt_pk_bf16_f32 v65, v66, v67
	v_add_f32_e32 v183, v71, v183
	v_cvt_pk_bf16_f32 v66, v68, v69
	v_cvt_pk_bf16_f32 v67, v70, v71
	v_mfma_f32_32x32x16_bf16 v[32:47], v[132:135], v[168:171], v[32:47]
	v_exp_f32_e32 v72, v72
	v_exp_f32_e32 v73, v73
	v_exp_f32_e32 v74, v74
	v_add_f32_e32 v182, v72, v182
	s_waitcnt lgkmcnt(4)
	v_mfma_f32_32x32x16_bf16 v[16:31], v[96:99], v[80:83], v[16:31]
	v_exp_f32_e32 v75, v75
	v_add_f32_e32 v183, v73, v183
	v_exp_f32_e32 v76, v76
	v_add_f32_e32 v182, v74, v182
	v_mfma_f32_32x32x16_bf16 v[0:15], v[100:103], v[80:83], v[0:15]
	v_exp_f32_e32 v77, v77
	v_add_f32_e32 v183, v75, v183
	v_exp_f32_e32 v78, v78
	v_add_f32_e32 v182, v76, v182
	v_mfma_f32_32x32x16_bf16 v[16:31], v[104:107], v[88:91], v[16:31]
	v_exp_f32_e32 v79, v79
	v_add_f32_e32 v183, v77, v183
	v_cvt_pk_bf16_f32 v72, v72, v73
	v_add_f32_e32 v182, v78, v182
	v_mfma_f32_32x32x16_bf16 v[0:15], v[108:111], v[88:91], v[0:15]
	v_cvt_pk_bf16_f32 v73, v74, v75
	v_add_f32_e32 v183, v79, v183
	v_cvt_pk_bf16_f32 v74, v76, v77
	v_cvt_pk_bf16_f32 v75, v78, v79
	s_waitcnt lgkmcnt(0)
	v_mfma_f32_32x32x16_bf16 v[16:31], v[112:115], v[64:67], v[16:31]
	v_max3_f32 v96, v48, v32, v49
	v_max3_f32 v97, v33, v50, v34
	v_max3_f32 v96, v51, v35, v96
	v_max3_f32 v97, v52, v36, v97
	v_mfma_f32_32x32x16_bf16 v[0:15], v[116:119], v[64:67], v[0:15]
	v_max3_f32 v96, v53, v37, v96
	v_max3_f32 v97, v54, v38, v97
	v_max3_f32 v96, v55, v39, v96
	v_max3_f32 v97, v56, v40, v97
	v_mfma_f32_32x32x16_bf16 v[16:31], v[120:123], v[72:75], v[16:31]
	v_max3_f32 v96, v57, v41, v96
	v_max3_f32 v97, v58, v42, v97
	v_max3_f32 v96, v59, v43, v96
	v_max3_f32 v97, v60, v44, v97
	v_mfma_f32_32x32x16_bf16 v[0:15], v[124:127], v[72:75], v[0:15]
	v_max3_f32 v96, v61, v45, v96
	v_max3_f32 v97, v62, v46, v97
	v_max3_f32 v96, v63, v47, v96
	v_max_f32_e32 v96, v96, v97
	v_lshl_add_u64 v[130:131], v[130:131], 0, s[84:85]
	v_lshl_add_u64 v[180:181], v[180:181], 0, s[84:85]
	s_mov_b32 s0, s45
	s_add_i32 s45, s45, 2
	s_cmp_lt_u32 s0, s19
	s_cbranch_scc1 .LBB0_238
	s_branch .Lg_fold
.Lg_fold:
	v_add_f32_e32 v173, v173, v182
	v_add_f32_e32 v173, v173, v183
	s_branch .LBB0_253
; DI unsigned pack2(float a, float b) { f32x2v f = {a, b}; bf16x2v v = __builtin_convertvector(f, bf16x2v); return __builtin_bit_cast(unsigned, v); }
; DI float xhalf(float v) { return __shfl_xor(v, 32); }
;   template <int PAR>
;   DI void step(int t, f32x16 (&cur)[2], f32x16 (&nxt)[2]) {
;     ...
;     if (__builtin_amdgcn_ballot_w64(mx > ATT_THR) != 0ull) {
;       asm volatile("" ::: "memory");
;       mx = fmaxf(mx, xhalf(mx));
;       const float want = mref + fmaxf(mx, 0.f);
;       const float mn = __uint_as_float(pack2(want, 0.f) << 16);
;       const float d = mn - mref;
;       const float alpha = __builtin_amdgcn_exp2f(-d);
;       mref = mn;
;       l *= alpha;
; #pragma unroll
;       for (int a = 0; a < 2; ++a)
; #pragma unroll
;         for (int i = 0; i < 16; ++i) { o[a][i] *= alpha; cur[a][i] -= d; nxt[a][i] -= d; }
;       u32x4 q4 = {h == 0 ? (pack2(-mn, 0.f) & 0xffffu) : 0u, 0u, 0u, 0u};
;       qm = __builtin_bit_cast(bf16x8, q4);
;     }
.Lgf_rareA:
	v_cmp_lt_i32_e64 s[0:1], v229, v228
	s_nop 1
	v_cndmask_b32_e64 v97, v227, v229, s[0:1]
	v_lshlrev_b32_e32 v97, 2, v97
	ds_bpermute_b32 v97, v97, v96
	s_waitcnt lgkmcnt(0)
	v_max3_f32 v96, v96, v97, 0
	v_add_f32_e32 v96, v178, v96
	v_cvt_pk_bf16_f32 v96, v96, 0
	v_lshlrev_b32_e32 v97, 16, v96
	v_sub_f32_e32 v96, v97, v178
	v_exp_f32_e64 v98, -v96
	v_pk_add_f32 v[48:49], v[48:49], v[96:97] op_sel_hi:[1,0] neg_lo:[0,1] neg_hi:[0,1]
	v_pk_add_f32 v[50:51], v[50:51], v[96:97] op_sel_hi:[1,0] neg_lo:[0,1] neg_hi:[0,1]
	v_pk_add_f32 v[52:53], v[52:53], v[96:97] op_sel_hi:[1,0] neg_lo:[0,1] neg_hi:[0,1]
	v_pk_add_f32 v[54:55], v[54:55], v[96:97] op_sel_hi:[1,0] neg_lo:[0,1] neg_hi:[0,1]
	v_pk_add_f32 v[56:57], v[56:57], v[96:97] op_sel_hi:[1,0] neg_lo:[0,1] neg_hi:[0,1]
	v_pk_add_f32 v[58:59], v[58:59], v[96:97] op_sel_hi:[1,0] neg_lo:[0,1] neg_hi:[0,1]
	v_pk_add_f32 v[60:61], v[60:61], v[96:97] op_sel_hi:[1,0] neg_lo:[0,1] neg_hi:[0,1]
	v_pk_add_f32 v[62:63], v[62:63], v[96:97] op_sel_hi:[1,0] neg_lo:[0,1] neg_hi:[0,1]
	v_pk_add_f32 v[32:33], v[32:33], v[96:97] op_sel_hi:[1,0] neg_lo:[0,1] neg_hi:[0,1]
	v_pk_add_f32 v[34:35], v[34:35], v[96:97] op_sel_hi:[1,0] neg_lo:[0,1] neg_hi:[0,1]
	v_pk_add_f32 v[36:37], v[36:37], v[96:97] op_sel_hi:[1,0] neg_lo:[0,1] neg_hi:[0,1]
	v_pk_add_f32 v[38:39], v[38:39], v[96:97] op_sel_hi:[1,0] neg_lo:[0,1] neg_hi:[0,1]
	v_pk_add_f32 v[40:41], v[40:41], v[96:97] op_sel_hi:[1,0] neg_lo:[0,1] neg_hi:[0,1]
	v_pk_add_f32 v[42:43], v[42:43], v[96:97] op_sel_hi:[1,0] neg_lo:[0,1] neg_hi:[0,1]
	v_pk_add_f32 v[44:45], v[44:45], v[96:97] op_sel_hi:[1,0] neg_lo:[0,1] neg_hi:[0,1]
	v_pk_add_f32 v[46:47], v[46:47], v[96:97] op_sel_hi:[1,0] neg_lo:[0,1] neg_hi:[0,1]
	v_xor_b32_e32 v96, 0x80000000, v97
	v_cvt_pk_bf16_f32 v96, v96, 0
	v_and_b32_e32 v96, 0xffff, v96
	v_mul_f32_e32 v173, v173, v98
	v_pk_mul_f32 v[182:183], v[182:183], v[98:99] op_sel_hi:[1,0]
	v_pk_mul_f32 v[30:31], v[30:31], v[98:99] op_sel_hi:[1,0]
	v_pk_mul_f32 v[28:29], v[28:29], v[98:99] op_sel_hi:[1,0]
	v_pk_mul_f32 v[26:27], v[26:27], v[98:99] op_sel_hi:[1,0]
	v_pk_mul_f32 v[24:25], v[24:25], v[98:99] op_sel_hi:[1,0]
	v_pk_mul_f32 v[22:23], v[22:23], v[98:99] op_sel_hi:[1,0]
	v_pk_mul_f32 v[20:21], v[20:21], v[98:99] op_sel_hi:[1,0]
	v_pk_mul_f32 v[18:19], v[18:19], v[98:99] op_sel_hi:[1,0]
	v_pk_mul_f32 v[16:17], v[16:17], v[98:99] op_sel_hi:[1,0]
	v_pk_mul_f32 v[14:15], v[14:15], v[98:99] op_sel_hi:[1,0]
	v_pk_mul_f32 v[12:13], v[12:13], v[98:99] op_sel_hi:[1,0]
	v_pk_mul_f32 v[10:11], v[10:11], v[98:99] op_sel_hi:[1,0]
	v_pk_mul_f32 v[8:9], v[8:9], v[98:99] op_sel_hi:[1,0]
	v_pk_mul_f32 v[6:7], v[6:7], v[98:99] op_sel_hi:[1,0]
	v_pk_mul_f32 v[4:5], v[4:5], v[98:99] op_sel_hi:[1,0]
	v_pk_mul_f32 v[2:3], v[2:3], v[98:99] op_sel_hi:[1,0]
	v_pk_mul_f32 v[0:1], v[0:1], v[98:99] op_sel_hi:[1,0]
	v_cndmask_b32_e64 v168, 0, v96, s[6:7]
	v_mov_b32_e32 v178, v97
	s_branch .Lg_rareA_ret
.Lgf_rareB:
	v_cmp_lt_i32_e64 s[0:1], v229, v228
	s_nop 1
	v_cndmask_b32_e64 v97, v227, v229, s[0:1]
	v_lshlrev_b32_e32 v97, 2, v97
	ds_bpermute_b32 v97, v97, v96
	s_waitcnt lgkmcnt(0)
	v_max3_f32 v96, v96, v97, 0
	v_add_f32_e32 v96, v178, v96
	v_cvt_pk_bf16_f32 v96, v96, 0
	v_lshlrev_b32_e32 v97, 16, v96
	v_sub_f32_e32 v96, v97, v178
	v_exp_f32_e64 v98, -v96
	v_pk_add_f32 v[80:81], v[80:81], v[96:97] op_sel_hi:[1,0] neg_lo:[0,1] neg_hi:[0,1]
	v_pk_add_f32 v[82:83], v[82:83], v[96:97] op_sel_hi:[1,0] neg_lo:[0,1] neg_hi:[0,1]
	v_pk_add_f32 v[84:85], v[84:85], v[96:97] op_sel_hi:[1,0] neg_lo:[0,1] neg_hi:[0,1]
	v_pk_add_f32 v[86:87], v[86:87], v[96:97] op_sel_hi:[1,0] neg_lo:[0,1] neg_hi:[0,1]
	v_pk_add_f32 v[88:89], v[88:89], v[96:97] op_sel_hi:[1,0] neg_lo:[0,1] neg_hi:[0,1]
	v_pk_add_f32 v[90:91], v[90:91], v[96:97] op_sel_hi:[1,0] neg_lo:[0,1] neg_hi:[0,1]
	v_pk_add_f32 v[92:93], v[92:93], v[96:97] op_sel_hi:[1,0] neg_lo:[0,1] neg_hi:[0,1]
	v_pk_add_f32 v[94:95], v[94:95], v[96:97] op_sel_hi:[1,0] neg_lo:[0,1] neg_hi:[0,1]
	v_pk_add_f32 v[64:65], v[64:65], v[96:97] op_sel_hi:[1,0] neg_lo:[0,1] neg_hi:[0,1]
	v_pk_add_f32 v[66:67], v[66:67], v[96:97] op_sel_hi:[1,0] neg_lo:[0,1] neg_hi:[0,1]
	v_pk_add_f32 v[68:69], v[68:69], v[96:97] op_sel_hi:[1,0] neg_lo:[0,1] neg_hi:[0,1]
	v_pk_add_f32 v[70:71], v[70:71], v[96:97] op_sel_hi:[1,0] neg_lo:[0,1] neg_hi:[0,1]
	v_pk_add_f32 v[72:73], v[72:73], v[96:97] op_sel_hi:[1,0] neg_lo:[0,1] neg_hi:[0,1]
	v_pk_add_f32 v[74:75], v[74:75], v[96:97] op_sel_hi:[1,0] neg_lo:[0,1] neg_hi:[0,1]
	v_pk_add_f32 v[76:77], v[76:77], v[96:97] op_sel_hi:[1,0] neg_lo:[0,1] neg_hi:[0,1]
	v_pk_add_f32 v[78:79], v[78:79], v[96:97] op_sel_hi:[1,0] neg_lo:[0,1] neg_hi:[0,1]
	v_xor_b32_e32 v96, 0x80000000, v97
	v_cvt_pk_bf16_f32 v96, v96, 0
	v_and_b32_e32 v96, 0xffff, v96
	v_mul_f32_e32 v173, v173, v98
	v_pk_mul_f32 v[182:183], v[182:183], v[98:99] op_sel_hi:[1,0]
	v_pk_mul_f32 v[30:31], v[30:31], v[98:99] op_sel_hi:[1,0]
	v_pk_mul_f32 v[28:29], v[28:29], v[98:99] op_sel_hi:[1,0]
	v_pk_mul_f32 v[26:27], v[26:27], v[98:99] op_sel_hi:[1,0]
	v_pk_mul_f32 v[24:25], v[24:25], v[98:99] op_sel_hi:[1,0]
	v_pk_mul_f32 v[22:23], v[22:23], v[98:99] op_sel_hi:[1,0]
	v_pk_mul_f32 v[20:21], v[20:21], v[98:99] op_sel_hi:[1,0]
	v_pk_mul_f32 v[18:19], v[18:19], v[98:99] op_sel_hi:[1,0]
	v_pk_mul_f32 v[16:17], v[16:17], v[98:99] op_sel_hi:[1,0]
	v_pk_mul_f32 v[14:15], v[14:15], v[98:99] op_sel_hi:[1,0]
	v_pk_mul_f32 v[12:13], v[12:13], v[98:99] op_sel_hi:[1,0]
	v_pk_mul_f32 v[10:11], v[10:11], v[98:99] op_sel_hi:[1,0]
	v_pk_mul_f32 v[8:9], v[8:9], v[98:99] op_sel_hi:[1,0]
	v_pk_mul_f32 v[6:7], v[6:7], v[98:99] op_sel_hi:[1,0]
	v_pk_mul_f32 v[4:5], v[4:5], v[98:99] op_sel_hi:[1,0]
	v_pk_mul_f32 v[2:3], v[2:3], v[98:99] op_sel_hi:[1,0]
	v_pk_mul_f32 v[0:1], v[0:1], v[98:99] op_sel_hi:[1,0]
	v_cndmask_b32_e64 v168, 0, v96, s[6:7]
	v_mov_b32_e32 v178, v97
	s_branch .Lg_rareB_ret

; DI int crow(int i, int h) { return (i & 3) + 8 * (i >> 2) + 4 * h; }
; DI int swap23(int r) { return (r & 0x13) | ((r & 4) << 1) | ((r & 8) >> 1); }
;   template <int PAR>
;   DI void step(int t, f32x16 (&cur)[2], f32x16 (&nxt)[2]) {
;     ...
;     float mx = fmaxf(cur[0][0], cur[1][0]);
; #pragma unroll
;     for (int i = 1; i < 16; ++i) mx = fmaxf(fmaxf(cur[0][i], cur[1][i]), mx);
;     if (__builtin_amdgcn_ballot_w64(mx > ATT_THR) != 0ull) {
; template <int DQK>
; DI void attn_item(const u16* __restrict__ Qb, int qpitch, const u16* __restrict__ Kb, int kpitch, const u16* __restrict__ KPEb,
;                   const u16* __restrict__ Vt, float* __restrict__ ssq, int rowq0, int rowk0, int nt, char* smem, int tid, bool dry) {
;     ...
;   f32x16 sa[2], sb[2];
;   c.gload_k(0); c.gload_v(0);
;   __syncthreads();
;   c.sstore_k(0); c.sstore_v(0);
;   if (nt > 1) c.gload_k(1);
;   __syncthreads();
;   c.qk(0, sa);
; #pragma unroll
;   for (int i = 0; i < 16; ++i) {
;     sa[0][i] = -1e30f;
;     if (swap23(crow(i, h)) < 16) sa[1][i] = -1e30f;
;   }
;   int t = 0;
;   for (; t + 1 < nt; t += 2) {
;     c.template step<0>(t, sa, sb);
;     c.template step<1>(t + 1, sb, sa);
;   }
;   if (t < nt) c.template step<0>(t, sa, sb);
.Lm_entry:
	v_mov_b32_e32 v181, 0
	v_mov_b32_e32 v182, 0
	v_mov_b32_e32 v183, 0
	v_mov_b32_e32 v238, 0
	v_mov_b32_e32 v239, 0
	s_sub_i32 s0, s44, 64
	s_ashr_i32 s1, s0, 31
	s_lshl_b64 s[20:21], s[0:1], 10
	s_lshl_b64 s[0:1], s[0:1], 6
	s_add_u32 s20, s26, s20
	s_addc_u32 s21, s27, s21
	s_add_u32 s44, s81, s0
	s_addc_u32 s45, s64, s1
	v_max3_f32 v112, v48, v32, v49
	v_max3_f32 v113, v33, v50, v34
	v_max3_f32 v112, v51, v35, v112
	v_max3_f32 v113, v52, v36, v113
	v_max3_f32 v112, v53, v37, v112
	v_max3_f32 v113, v54, v38, v113
	v_max3_f32 v112, v55, v39, v112
	v_max3_f32 v113, v56, v40, v113
	v_max3_f32 v112, v57, v41, v112
	v_max3_f32 v113, v58, v42, v113
	v_max3_f32 v112, v59, v43, v112
	v_max3_f32 v113, v60, v44, v113
	v_max3_f32 v112, v61, v45, v112
	v_max3_f32 v113, v62, v46, v113
	v_max3_f32 v112, v63, v47, v112
	v_max_f32_e32 v112, v112, v113
	v_and_b32_e32 v114, 0x7fff, v180
	v_cmp_ne_u32_e32 vcc, 0, v114
	s_cbranch_vccnz .LBB0_268

;   DI void gload_k(int t) {
;     const int row0 = rowk0 + t * 64;
;     const u16* kt = Kb + (size_t)row0 * kpitch;
;     const u16* pt = KPEb + (size_t)row0 * 32;
; #pragma unroll
;     for (int q = 0; q < NKL; ++q) {
;       const int c = tid + 256 * q, cc = c % KCH;
;       rk[q] = ldg16(((DQK == 96 && cc >= 8) ? pt : kt) + koff[q]);
;     }
;   }
.Lmf_rareA_ret:
	s_add_i32 s0, s31, -1
	s_cmp_ge_u32 s0, s19
	s_cselect_b64 s[14:15], -1, 0
	s_cbranch_scc1 .Lmf_skipKA
	v_mov_b32_e32 v100, s21
	v_mov_b32_e32 v101, s45
	v_mov_b32_e32 v102, s20
	v_mov_b32_e32 v103, s44
	v_cndmask_b32_e64 v105, v100, v101, s[8:9]
	v_cndmask_b32_e64 v104, v102, v103, s[8:9]
	v_lshl_add_u64 v[104:105], v[200:201], 1, v[104:105]
	global_load_dwordx4 v[160:163], v[104:105], off
	v_cndmask_b32_e64 v107, v100, v101, s[10:11]
	v_cndmask_b32_e64 v106, v102, v103, s[10:11]
	v_lshl_add_u64 v[106:107], v[202:203], 1, v[106:107]
	global_load_dwordx4 v[164:167], v[106:107], off
	v_cndmask_b32_e64 v109, v100, v101, s[12:13]
	v_cndmask_b32_e64 v108, v102, v103, s[12:13]
	v_lshl_add_u64 v[108:109], v[204:205], 1, v[108:109]
	global_load_dwordx4 v[168:171], v[108:109], off
	s_add_u32 s20, s20, 0x10000
	s_addc_u32 s21, s21, 0
	s_add_u32 s44, s44, 0x1000
	s_addc_u32 s45, s45, 0
; #define MFMA(a, b, c) __builtin_amdgcn_mfma_f32_32x32x16_bf16((a), (b), (c), 0, 0, 0)
; DI unsigned pack2(float a, float b) { f32x2v f = {a, b}; bf16x2v v = __builtin_convertvector(f, bf16x2v); return __builtin_bit_cast(unsigned, v); }
; DI float xhalf(float v) { return __shfl_xor(v, 32); }
;   template <int PAR>
;   DI void step(int t, f32x16 (&cur)[2], f32x16 (&nxt)[2]) {
;     if (t + 1 < nt) sstore_k(PAR ^ 1);
;     if (t > 0) sstore_v(PAR);
;     __syncthreads();
;     if (t + 1 < nt) qk(PAR ^ 1, nxt);
;     float mx = fmaxf(cur[0][0], cur[1][0]);
; #pragma unroll
;     for (int i = 1; i < 16; ++i) mx = fmaxf(fmaxf(cur[0][i], cur[1][i]), mx);
;     if (__builtin_amdgcn_ballot_w64(mx > ATT_THR) != 0ull) {
;       asm volatile("" ::: "memory");
;       mx = fmaxf(mx, xhalf(mx));
;       const float want = mref + fmaxf(mx, 0.f);
;       const float mn = __uint_as_float(pack2(want, 0.f) << 16);
;       const float d = mn - mref;
;       const float alpha = __builtin_amdgcn_exp2f(-d);
;       mref = mn;
;       l *= alpha;
; #pragma unroll
;       for (int a = 0; a < 2; ++a)
; #pragma unroll
;         for (int i = 0; i < 16; ++i) { o[a][i] *= alpha; cur[a][i] -= d; nxt[a][i] -= d; }
;       u32x4 q4 = {h == 0 ? (pack2(-mn, 0.f) & 0xffffu) : 0u, 0u, 0u, 0u};
;       qm = __builtin_bit_cast(bf16x8, q4);
;     }
;     float psum = 0.f;
; #pragma unroll
;     for (int kb2 = 0; kb2 < 2; ++kb2)
; #pragma unroll
;       for (int i = 0; i < 16; ++i) { const float pv = __builtin_amdgcn_exp2f(cur[kb2][i]); cur[kb2][i] = pv; psum += pv; }
;     l += psum;
;     if (t + 2 < nt) gload_k(t + 2);
;     if (t + 1 < nt) gload_v(t + 1);
;     const u16* vb = sV + PAR * VBUF + r * GP + h * 8;
; #pragma unroll
;     for (int kb2 = 0; kb2 < 2; ++kb2)
; #pragma unroll
;       for (int s2 = 0; s2 < 2; ++s2) {
;         u32x4 pk = {pack2(cur[kb2][8 * s2], cur[kb2][8 * s2 + 1]), pack2(cur[kb2][8 * s2 + 2], cur[kb2][8 * s2 + 3]),
;                     pack2(cur[kb2][8 * s2 + 4], cur[kb2][8 * s2 + 5]), pack2(cur[kb2][8 * s2 + 6], cur[kb2][8 * s2 + 7])};
;         const bf16x8 pf = __builtin_bit_cast(bf16x8, pk);
; #pragma unroll
;         for (int db = 0; db < 2; ++db) {
;           const bf16x8 a = *(const bf16x8*)(vb + db * 32 * GP + kb2 * 32 + s2 * 16);
;           o[db] = MFMA(a, pf, o[db]);
;         }
;       }
;   }
.Lmf_skipKA:
	global_load_dwordx4 v[172:175], v[130:131], off offset:-128
	global_load_dwordx4 v[176:179], v[220:221], off offset:-128
	v_exp_f32_e32 v48, v48
	v_exp_f32_e32 v49, v49
	v_exp_f32_e32 v50, v50
	v_add_f32_e32 v238, v48, v238
	v_exp_f32_e32 v51, v51
	v_add_f32_e32 v239, v49, v239
	v_exp_f32_e32 v52, v52
	v_add_f32_e32 v238, v50, v238
	v_exp_f32_e32 v53, v53
	v_add_f32_e32 v239, v51, v239
	s_waitcnt lgkmcnt(0)
	s_barrier
	ds_read_b128 v[96:99], v236 offset:13312
	ds_read_b128 v[100:103], v236 offset:19968
	ds_read_b128 v[104:107], v236 offset:13344
	ds_read_b128 v[108:111], v236 offset:20000
	ds_read_b128 v[112:115], v236 offset:13376
	ds_read_b128 v[116:119], v236 offset:20032
	ds_read_b128 v[120:123], v236 offset:13408
	ds_read_b128 v[124:127], v236 offset:20064
	v_exp_f32_e32 v54, v54
	v_add_f32_e32 v238, v52, v238
	v_exp_f32_e32 v55, v55
	v_add_f32_e32 v239, v53, v239
	v_cvt_pk_bf16_f32 v48, v48, v49
	v_add_f32_e32 v238, v54, v238
	s_waitcnt lgkmcnt(6)
	v_mfma_f32_32x32x16_bf16 v[80:95], v[96:99], v[136:139], 0
	ds_read_b128 v[96:99], v236 offset:13440
	v_cvt_pk_bf16_f32 v49, v50, v51
	v_add_f32_e32 v239, v55, v239
	v_cvt_pk_bf16_f32 v50, v52, v53
	v_cvt_pk_bf16_f32 v51, v54, v55
	v_mfma_f32_32x32x16_bf16 v[64:79], v[100:103], v[136:139], 0
	ds_read_b128 v[100:103], v236 offset:20096
	v_exp_f32_e32 v56, v56
	v_exp_f32_e32 v57, v57
	v_exp_f32_e32 v58, v58
	v_add_f32_e32 v238, v56, v238
	s_waitcnt lgkmcnt(6)
	v_mfma_f32_32x32x16_bf16 v[80:95], v[104:107], v[140:143], v[80:95]
	ds_read_b128 v[104:107], v236 offset:13472
	v_exp_f32_e32 v59, v59
	v_add_f32_e32 v239, v57, v239
	v_exp_f32_e32 v60, v60
	v_add_f32_e32 v238, v58, v238
	v_mfma_f32_32x32x16_bf16 v[64:79], v[108:111], v[140:143], v[64:79]
	ds_read_b128 v[108:111], v236 offset:20128
	v_exp_f32_e32 v61, v61
	v_add_f32_e32 v239, v59, v239
	v_exp_f32_e32 v62, v62
	v_add_f32_e32 v238, v60, v238
	s_waitcnt lgkmcnt(6)
	v_mfma_f32_32x32x16_bf16 v[80:95], v[112:115], v[144:147], v[80:95]
	ds_read_b128 v[112:115], v197 offset:26624
	v_exp_f32_e32 v63, v63
	v_add_f32_e32 v239, v61, v239
	v_cvt_pk_bf16_f32 v56, v56, v57
	v_add_f32_e32 v238, v62, v238
	v_mfma_f32_32x32x16_bf16 v[64:79], v[116:119], v[144:147], v[64:79]
	ds_read_b128 v[116:119], v197 offset:31232
	v_cvt_pk_bf16_f32 v57, v58, v59
	v_add_f32_e32 v239, v63, v239
	v_cvt_pk_bf16_f32 v58, v60, v61
	v_cvt_pk_bf16_f32 v59, v62, v63
	s_waitcnt lgkmcnt(6)
	v_mfma_f32_32x32x16_bf16 v[80:95], v[120:123], v[148:151], v[80:95]
	ds_read_b128 v[120:123], v197 offset:26656
	v_exp_f32_e32 v32, v32
	v_exp_f32_e32 v33, v33
	v_exp_f32_e32 v34, v34
	v_add_f32_e32 v238, v32, v238
	v_mfma_f32_32x32x16_bf16 v[64:79], v[124:127], v[148:151], v[64:79]
	ds_read_b128 v[124:127], v197 offset:31264
	v_exp_f32_e32 v35, v35
	v_add_f32_e32 v239, v33, v239
	v_exp_f32_e32 v36, v36
	v_add_f32_e32 v238, v34, v238
	s_waitcnt lgkmcnt(6)
	v_mfma_f32_32x32x16_bf16 v[80:95], v[96:99], v[152:155], v[80:95]
	ds_read_b128 v[96:99], v197 offset:26688
	v_exp_f32_e32 v37, v37
	v_add_f32_e32 v239, v35, v239
	v_exp_f32_e32 v38, v38
	v_add_f32_e32 v238, v36, v238
	v_mfma_f32_32x32x16_bf16 v[64:79], v[100:103], v[152:155], v[64:79]
	ds_read_b128 v[100:103], v197 offset:31296
	v_exp_f32_e32 v39, v39
	v_add_f32_e32 v239, v37, v239
	v_cvt_pk_bf16_f32 v32, v32, v33
	v_add_f32_e32 v238, v38, v238
	s_waitcnt lgkmcnt(6)
	v_mfma_f32_32x32x16_bf16 v[80:95], v[104:107], v[156:159], v[80:95]
	ds_read_b128 v[104:107], v197 offset:26720
	v_cvt_pk_bf16_f32 v33, v34, v35
	v_add_f32_e32 v239, v39, v239
	v_cvt_pk_bf16_f32 v34, v36, v37
	v_cvt_pk_bf16_f32 v35, v38, v39
	v_mfma_f32_32x32x16_bf16 v[64:79], v[108:111], v[156:159], v[64:79]
	ds_read_b128 v[108:111], v197 offset:31328
	v_exp_f32_e32 v40, v40
	v_exp_f32_e32 v41, v41
	v_exp_f32_e32 v42, v42
	v_add_f32_e32 v238, v40, v238
	s_waitcnt lgkmcnt(4)
	v_mfma_f32_32x32x16_bf16 v[16:31], v[112:115], v[48:51], v[16:31]
	v_exp_f32_e32 v43, v43
	v_add_f32_e32 v239, v41, v239
	v_exp_f32_e32 v44, v44
	v_add_f32_e32 v238, v42, v238
	v_mfma_f32_32x32x16_bf16 v[0:15], v[116:119], v[48:51], v[0:15]
	v_exp_f32_e32 v45, v45
	v_add_f32_e32 v239, v43, v239
	v_exp_f32_e32 v46, v46
	v_add_f32_e32 v238, v44, v238
	v_mfma_f32_32x32x16_bf16 v[16:31], v[120:123], v[56:59], v[16:31]
	v_exp_f32_e32 v47, v47
	v_add_f32_e32 v239, v45, v239
	v_cvt_pk_bf16_f32 v40, v40, v41
	v_add_f32_e32 v238, v46, v238
	v_mfma_f32_32x32x16_bf16 v[0:15], v[124:127], v[56:59], v[0:15]
	v_cvt_pk_bf16_f32 v41, v42, v43
	v_add_f32_e32 v239, v47, v239
	v_cvt_pk_bf16_f32 v42, v44, v45
	v_cvt_pk_bf16_f32 v43, v46, v47
	s_waitcnt lgkmcnt(0)
	v_mfma_f32_32x32x16_bf16 v[16:31], v[96:99], v[32:35], v[16:31]
	v_max3_f32 v112, v80, v64, v81
	v_max3_f32 v113, v65, v82, v66
	v_max3_f32 v112, v83, v67, v112
	v_max3_f32 v113, v84, v68, v113
	v_mfma_f32_32x32x16_bf16 v[0:15], v[100:103], v[32:35], v[0:15]
	v_max3_f32 v112, v85, v69, v112
	v_max3_f32 v113, v86, v70, v113
	v_max3_f32 v112, v87, v71, v112
	v_max3_f32 v113, v88, v72, v113
	v_mfma_f32_32x32x16_bf16 v[16:31], v[104:107], v[40:43], v[16:31]
	v_max3_f32 v112, v89, v73, v112
	v_max3_f32 v113, v90, v74, v113
	v_max3_f32 v112, v91, v75, v112
	v_max3_f32 v113, v92, v76, v113
	v_mfma_f32_32x32x16_bf16 v[0:15], v[108:111], v[40:43], v[0:15]
	v_max3_f32 v112, v93, v77, v112
	v_max3_f32 v113, v94, v78, v113
	v_max3_f32 v112, v95, v79, v112
	v_max_f32_e32 v112, v112, v113
	s_waitcnt vmcnt(0)
	ds_write_b128 v250, v[160:163]
	ds_write_b128 v251, v[164:167]
	ds_write_b128 v252, v[168:171]
	ds_write_b128 v194, v[172:175] offset:35840
	ds_write_b128 v196, v[176:179] offset:35840
	v_cmp_lt_f32_e32 vcc, s65, v112
	s_cbranch_vccnz .Lmf_rareB
.Lmf_rareB_ret:
	s_cmp_ge_u32 s31, s19
	s_cbranch_scc1 .Lmf_skipKB
	v_mov_b32_e32 v100, s21
	v_mov_b32_e32 v101, s45
	v_mov_b32_e32 v102, s20
	v_mov_b32_e32 v103, s44
	v_cndmask_b32_e64 v105, v100, v101, s[8:9]
	v_cndmask_b32_e64 v104, v102, v103, s[8:9]
	v_lshl_add_u64 v[104:105], v[200:201], 1, v[104:105]
	global_load_dwordx4 v[160:163], v[104:105], off
	v_cndmask_b32_e64 v107, v100, v101, s[10:11]
	v_cndmask_b32_e64 v106, v102, v103, s[10:11]
	v_lshl_add_u64 v[106:107], v[202:203], 1, v[106:107]
	global_load_dwordx4 v[164:167], v[106:107], off
	v_cndmask_b32_e64 v109, v100, v101, s[12:13]
	v_cndmask_b32_e64 v108, v102, v103, s[12:13]
	v_lshl_add_u64 v[108:109], v[204:205], 1, v[108:109]
	global_load_dwordx4 v[168:171], v[108:109], off
	s_add_u32 s20, s20, 0x10000
	s_addc_u32 s21, s21, 0
	s_add_u32 s44, s44, 0x1000
	s_addc_u32 s45, s45, 0

; #define MFMA(a, b, c) __builtin_amdgcn_mfma_f32_32x32x16_bf16((a), (b), (c), 0, 0, 0)
; DI unsigned pack2(float a, float b) { f32x2v f = {a, b}; bf16x2v v = __builtin_convertvector(f, bf16x2v); return __builtin_bit_cast(unsigned, v); }
; DI float xhalf(float v) { return __shfl_xor(v, 32); }
;   template <int PAR>
;   DI void step(int t, f32x16 (&cur)[2], f32x16 (&nxt)[2]) {
;     if (t + 1 < nt) sstore_k(PAR ^ 1);
;     if (t > 0) sstore_v(PAR);
;     __syncthreads();
;     if (t + 1 < nt) qk(PAR ^ 1, nxt);
;     float mx = fmaxf(cur[0][0], cur[1][0]);
; #pragma unroll
;     for (int i = 1; i < 16; ++i) mx = fmaxf(fmaxf(cur[0][i], cur[1][i]), mx);
;     if (__builtin_amdgcn_ballot_w64(mx > ATT_THR) != 0ull) {
;       asm volatile("" ::: "memory");
;       mx = fmaxf(mx, xhalf(mx));
;       const float want = mref + fmaxf(mx, 0.f);
;       const float mn = __uint_as_float(pack2(want, 0.f) << 16);
;       const float d = mn - mref;
;       const float alpha = __builtin_amdgcn_exp2f(-d);
;       mref = mn;
;       l *= alpha;
; #pragma unroll
;       for (int a = 0; a < 2; ++a)
; #pragma unroll
;         for (int i = 0; i < 16; ++i) { o[a][i] *= alpha; cur[a][i] -= d; nxt[a][i] -= d; }
;       u32x4 q4 = {h == 0 ? (pack2(-mn, 0.f) & 0xffffu) : 0u, 0u, 0u, 0u};
;       qm = __builtin_bit_cast(bf16x8, q4);
;     }
;     float psum = 0.f;
; #pragma unroll
;     for (int kb2 = 0; kb2 < 2; ++kb2)
; #pragma unroll
;       for (int i = 0; i < 16; ++i) { const float pv = __builtin_amdgcn_exp2f(cur[kb2][i]); cur[kb2][i] = pv; psum += pv; }
;     l += psum;
;     if (t + 2 < nt) gload_k(t + 2);
;     if (t + 1 < nt) gload_v(t + 1);
;     const u16* vb = sV + PAR * VBUF + r * GP + h * 8;
; #pragma unroll
;     for (int kb2 = 0; kb2 < 2; ++kb2)
; #pragma unroll
;       for (int s2 = 0; s2 < 2; ++s2) {
;         u32x4 pk = {pack2(cur[kb2][8 * s2], cur[kb2][8 * s2 + 1]), pack2(cur[kb2][8 * s2 + 2], cur[kb2][8 * s2 + 3]),
;                     pack2(cur[kb2][8 * s2 + 4], cur[kb2][8 * s2 + 5]), pack2(cur[kb2][8 * s2 + 6], cur[kb2][8 * s2 + 7])};
;         const bf16x8 pf = __builtin_bit_cast(bf16x8, pk);
; #pragma unroll
;         for (int db = 0; db < 2; ++db) {
;           const bf16x8 a = *(const bf16x8*)(vb + db * 32 * GP + kb2 * 32 + s2 * 16);
;           o[db] = MFMA(a, pf, o[db]);
;         }
;       }
;   }
.Lmf_skipVB:
	v_exp_f32_e32 v80, v80
	v_exp_f32_e32 v81, v81
	v_exp_f32_e32 v82, v82
	v_add_f32_e32 v238, v80, v238
	v_exp_f32_e32 v83, v83
	v_add_f32_e32 v239, v81, v239
	v_exp_f32_e32 v84, v84
	v_add_f32_e32 v238, v82, v238
	v_exp_f32_e32 v85, v85
	v_add_f32_e32 v239, v83, v239
	s_waitcnt lgkmcnt(0)
	s_barrier
	ds_read_b128 v[96:99], v236
	ds_read_b128 v[100:103], v236 offset:6656
	ds_read_b128 v[104:107], v236 offset:32
	ds_read_b128 v[108:111], v236 offset:6688
	ds_read_b128 v[112:115], v236 offset:64
	ds_read_b128 v[116:119], v236 offset:6720
	ds_read_b128 v[120:123], v236 offset:96
	ds_read_b128 v[124:127], v236 offset:6752
	v_exp_f32_e32 v86, v86
	v_add_f32_e32 v238, v84, v238
	v_exp_f32_e32 v87, v87
	v_add_f32_e32 v239, v85, v239
	v_cvt_pk_bf16_f32 v80, v80, v81
	v_add_f32_e32 v238, v86, v238
	s_waitcnt lgkmcnt(6)
	v_mfma_f32_32x32x16_bf16 v[48:63], v[96:99], v[136:139], 0
	ds_read_b128 v[96:99], v236 offset:128
	v_cvt_pk_bf16_f32 v81, v82, v83
	v_add_f32_e32 v239, v87, v239
	v_cvt_pk_bf16_f32 v82, v84, v85
	v_cvt_pk_bf16_f32 v83, v86, v87
	v_mfma_f32_32x32x16_bf16 v[32:47], v[100:103], v[136:139], 0
	ds_read_b128 v[100:103], v236 offset:6784
	v_exp_f32_e32 v88, v88
	v_exp_f32_e32 v89, v89
	v_exp_f32_e32 v90, v90
	v_add_f32_e32 v238, v88, v238
	s_waitcnt lgkmcnt(6)
	v_mfma_f32_32x32x16_bf16 v[48:63], v[104:107], v[140:143], v[48:63]
	ds_read_b128 v[104:107], v236 offset:160
	v_exp_f32_e32 v91, v91
	v_add_f32_e32 v239, v89, v239
	v_exp_f32_e32 v92, v92
	v_add_f32_e32 v238, v90, v238
	v_mfma_f32_32x32x16_bf16 v[32:47], v[108:111], v[140:143], v[32:47]
	ds_read_b128 v[108:111], v236 offset:6816
	v_exp_f32_e32 v93, v93
	v_add_f32_e32 v239, v91, v239
	v_exp_f32_e32 v94, v94
	v_add_f32_e32 v238, v92, v238
	s_waitcnt lgkmcnt(6)
	v_mfma_f32_32x32x16_bf16 v[48:63], v[112:115], v[144:147], v[48:63]
	ds_read_b128 v[112:115], v197 offset:35840
	v_exp_f32_e32 v95, v95
	v_add_f32_e32 v239, v93, v239
	v_cvt_pk_bf16_f32 v88, v88, v89
	v_add_f32_e32 v238, v94, v238
	v_mfma_f32_32x32x16_bf16 v[32:47], v[116:119], v[144:147], v[32:47]
	ds_read_b128 v[116:119], v197 offset:40448
	v_cvt_pk_bf16_f32 v89, v90, v91
	v_add_f32_e32 v239, v95, v239
	v_cvt_pk_bf16_f32 v90, v92, v93
	v_cvt_pk_bf16_f32 v91, v94, v95
	s_waitcnt lgkmcnt(6)
	v_mfma_f32_32x32x16_bf16 v[48:63], v[120:123], v[148:151], v[48:63]
	ds_read_b128 v[120:123], v197 offset:35872
	v_exp_f32_e32 v64, v64
	v_exp_f32_e32 v65, v65
	v_exp_f32_e32 v66, v66
	v_add_f32_e32 v238, v64, v238
	v_mfma_f32_32x32x16_bf16 v[32:47], v[124:127], v[148:151], v[32:47]
	ds_read_b128 v[124:127], v197 offset:40480
	v_exp_f32_e32 v67, v67
	v_add_f32_e32 v239, v65, v239
	v_exp_f32_e32 v68, v68
	v_add_f32_e32 v238, v66, v238
	s_waitcnt lgkmcnt(6)
	v_mfma_f32_32x32x16_bf16 v[48:63], v[96:99], v[152:155], v[48:63]
	ds_read_b128 v[96:99], v197 offset:35904
	v_exp_f32_e32 v69, v69
	v_add_f32_e32 v239, v67, v239
	v_exp_f32_e32 v70, v70
	v_add_f32_e32 v238, v68, v238
	v_mfma_f32_32x32x16_bf16 v[32:47], v[100:103], v[152:155], v[32:47]
	ds_read_b128 v[100:103], v197 offset:40512
	v_exp_f32_e32 v71, v71
	v_add_f32_e32 v239, v69, v239
	v_cvt_pk_bf16_f32 v64, v64, v65
	v_add_f32_e32 v238, v70, v238
	s_waitcnt lgkmcnt(6)
	v_mfma_f32_32x32x16_bf16 v[48:63], v[104:107], v[156:159], v[48:63]
	ds_read_b128 v[104:107], v197 offset:35936
	v_cvt_pk_bf16_f32 v65, v66, v67
	v_add_f32_e32 v239, v71, v239
	v_cvt_pk_bf16_f32 v66, v68, v69
	v_cvt_pk_bf16_f32 v67, v70, v71
	v_mfma_f32_32x32x16_bf16 v[32:47], v[108:111], v[156:159], v[32:47]
	ds_read_b128 v[108:111], v197 offset:40544
	v_exp_f32_e32 v72, v72
	v_exp_f32_e32 v73, v73
	v_exp_f32_e32 v74, v74
	v_add_f32_e32 v238, v72, v238
	s_waitcnt lgkmcnt(4)
	v_mfma_f32_32x32x16_bf16 v[16:31], v[112:115], v[80:83], v[16:31]
	v_exp_f32_e32 v75, v75
	v_add_f32_e32 v239, v73, v239
	v_exp_f32_e32 v76, v76
	v_add_f32_e32 v238, v74, v238
	v_mfma_f32_32x32x16_bf16 v[0:15], v[116:119], v[80:83], v[0:15]
	v_exp_f32_e32 v77, v77
	v_add_f32_e32 v239, v75, v239
	v_exp_f32_e32 v78, v78
	v_add_f32_e32 v238, v76, v238
	v_mfma_f32_32x32x16_bf16 v[16:31], v[120:123], v[88:91], v[16:31]
	v_exp_f32_e32 v79, v79
	v_add_f32_e32 v239, v77, v239
	v_cvt_pk_bf16_f32 v72, v72, v73
	v_add_f32_e32 v238, v78, v238
	v_mfma_f32_32x32x16_bf16 v[0:15], v[124:127], v[88:91], v[0:15]
	v_cvt_pk_bf16_f32 v73, v74, v75
	v_add_f32_e32 v239, v79, v239
	v_cvt_pk_bf16_f32 v74, v76, v77
	v_cvt_pk_bf16_f32 v75, v78, v79
	s_waitcnt lgkmcnt(0)
	v_mfma_f32_32x32x16_bf16 v[16:31], v[96:99], v[64:67], v[16:31]
	v_max3_f32 v112, v48, v32, v49
	v_max3_f32 v113, v33, v50, v34
	v_max3_f32 v112, v51, v35, v112
	v_max3_f32 v113, v52, v36, v113
	v_mfma_f32_32x32x16_bf16 v[0:15], v[100:103], v[64:67], v[0:15]
	v_max3_f32 v112, v53, v37, v112
	v_max3_f32 v113, v54, v38, v113
	v_max3_f32 v112, v55, v39, v112
	v_max3_f32 v113, v56, v40, v113
	v_mfma_f32_32x32x16_bf16 v[16:31], v[104:107], v[72:75], v[16:31]
	v_max3_f32 v112, v57, v41, v112
	v_max3_f32 v113, v58, v42, v113
	v_max3_f32 v112, v59, v43, v112
	v_max3_f32 v113, v60, v44, v113
	v_mfma_f32_32x32x16_bf16 v[0:15], v[108:111], v[72:75], v[0:15]
	v_max3_f32 v112, v61, v45, v112
	v_max3_f32 v113, v62, v46, v113
	v_max3_f32 v112, v63, v47, v112
	v_max_f32_e32 v112, v112, v113
	v_lshl_add_u64 v[130:131], v[130:131], 0, s[84:85]
	v_lshl_add_u64 v[220:221], v[220:221], 0, s[84:85]
	s_mov_b32 s0, s31
	s_add_i32 s31, s31, 2
	s_cmp_lt_u32 s0, s19
	s_cbranch_scc1 .Lmf_top
	s_branch .Lm_fold

; #define MFMA(a, b, c) __builtin_amdgcn_mfma_f32_32x32x16_bf16((a), (b), (c), 0, 0, 0)
; DI unsigned pack2(float a, float b) { f32x2v f = {a, b}; bf16x2v v = __builtin_convertvector(f, bf16x2v); return __builtin_bit_cast(unsigned, v); }
; DI float xhalf(float v) { return __shfl_xor(v, 32); }
;   template <int PAR>
;   DI void step(int t, f32x16 (&cur)[2], f32x16 (&nxt)[2]) {
;     if (t + 1 < nt) sstore_k(PAR ^ 1);
;     if (t > 0) sstore_v(PAR);
;     __syncthreads();
;     if (t + 1 < nt) qk(PAR ^ 1, nxt);
;     float mx = fmaxf(cur[0][0], cur[1][0]);
; #pragma unroll
;     for (int i = 1; i < 16; ++i) mx = fmaxf(fmaxf(cur[0][i], cur[1][i]), mx);
;     if (__builtin_amdgcn_ballot_w64(mx > ATT_THR) != 0ull) {
;       asm volatile("" ::: "memory");
;       mx = fmaxf(mx, xhalf(mx));
;       const float want = mref + fmaxf(mx, 0.f);
;       const float mn = __uint_as_float(pack2(want, 0.f) << 16);
;       const float d = mn - mref;
;       const float alpha = __builtin_amdgcn_exp2f(-d);
;       mref = mn;
;       l *= alpha;
; #pragma unroll
;       for (int a = 0; a < 2; ++a)
; #pragma unroll
;         for (int i = 0; i < 16; ++i) { o[a][i] *= alpha; cur[a][i] -= d; nxt[a][i] -= d; }
;       u32x4 q4 = {h == 0 ? (pack2(-mn, 0.f) & 0xffffu) : 0u, 0u, 0u, 0u};
;       qm = __builtin_bit_cast(bf16x8, q4);
;     }
;     float psum = 0.f;
; #pragma unroll
;     for (int kb2 = 0; kb2 < 2; ++kb2)
; #pragma unroll
;       for (int i = 0; i < 16; ++i) { const float pv = __builtin_amdgcn_exp2f(cur[kb2][i]); cur[kb2][i] = pv; psum += pv; }
;     l += psum;
;     if (t + 2 < nt) gload_k(t + 2);
;     if (t + 1 < nt) gload_v(t + 1);
;     const u16* vb = sV + PAR * VBUF + r * GP + h * 8;
; #pragma unroll
;     for (int kb2 = 0; kb2 < 2; ++kb2)
; #pragma unroll
;       for (int s2 = 0; s2 < 2; ++s2) {
;         u32x4 pk = {pack2(cur[kb2][8 * s2], cur[kb2][8 * s2 + 1]), pack2(cur[kb2][8 * s2 + 2], cur[kb2][8 * s2 + 3]),
;                     pack2(cur[kb2][8 * s2 + 4], cur[kb2][8 * s2 + 5]), pack2(cur[kb2][8 * s2 + 6], cur[kb2][8 * s2 + 7])};
;         const bf16x8 pf = __builtin_bit_cast(bf16x8, pk);
; #pragma unroll
;         for (int db = 0; db < 2; ++db) {
;           const bf16x8 a = *(const bf16x8*)(vb + db * 32 * GP + kb2 * 32 + s2 * 16);
;           o[db] = MFMA(a, pf, o[db]);
;         }
;       }
;   }
.Lm_skipKA:
	global_load_dwordx4 v[172:175], v[130:131], off offset:-128
	global_load_dwordx4 v[176:179], v[220:221], off offset:-128
	v_exp_f32_e32 v48, v48
	v_exp_f32_e32 v49, v49
	v_exp_f32_e32 v50, v50
	v_add_f32_e32 v238, v48, v238
	v_exp_f32_e32 v51, v51
	v_add_f32_e32 v239, v49, v239
	v_exp_f32_e32 v52, v52
	v_add_f32_e32 v238, v50, v238
	v_exp_f32_e32 v53, v53
	v_add_f32_e32 v239, v51, v239
	s_waitcnt lgkmcnt(0)
	s_barrier
	ds_read_b128 v[96:99], v236 offset:13312
	ds_read_b128 v[100:103], v236 offset:19968
	ds_read_b128 v[104:107], v236 offset:13344
	ds_read_b128 v[108:111], v236 offset:20000
	ds_read_b128 v[112:115], v236 offset:13376
	ds_read_b128 v[116:119], v236 offset:20032
	ds_read_b128 v[120:123], v236 offset:13408
	ds_read_b128 v[124:127], v236 offset:20064
	v_exp_f32_e32 v54, v54
	v_add_f32_e32 v238, v52, v238
	v_exp_f32_e32 v55, v55
	v_add_f32_e32 v239, v53, v239
	v_cvt_pk_bf16_f32 v48, v48, v49
	v_add_f32_e32 v238, v54, v238
	s_waitcnt lgkmcnt(6)
	v_mfma_f32_32x32x16_bf16 v[80:95], v[96:99], v[136:139], 0
	ds_read_b128 v[96:99], v236 offset:13440
	v_cvt_pk_bf16_f32 v49, v50, v51
	v_add_f32_e32 v239, v55, v239
	v_cvt_pk_bf16_f32 v50, v52, v53
	v_cvt_pk_bf16_f32 v51, v54, v55
	v_mfma_f32_32x32x16_bf16 v[64:79], v[100:103], v[136:139], 0
	ds_read_b128 v[100:103], v236 offset:20096
	v_exp_f32_e32 v56, v56
	v_exp_f32_e32 v57, v57
	v_exp_f32_e32 v58, v58
	v_add_f32_e32 v238, v56, v238
	s_waitcnt lgkmcnt(6)
	v_mfma_f32_32x32x16_bf16 v[80:95], v[104:107], v[140:143], v[80:95]
	ds_read_b128 v[104:107], v236 offset:13472
	v_exp_f32_e32 v59, v59
	v_add_f32_e32 v239, v57, v239
	v_exp_f32_e32 v60, v60
	v_add_f32_e32 v238, v58, v238
	v_mfma_f32_32x32x16_bf16 v[64:79], v[108:111], v[140:143], v[64:79]
	ds_read_b128 v[108:111], v236 offset:20128
	v_exp_f32_e32 v61, v61
	v_add_f32_e32 v239, v59, v239
	v_exp_f32_e32 v62, v62
	v_add_f32_e32 v238, v60, v238
	s_waitcnt lgkmcnt(6)
	v_mfma_f32_32x32x16_bf16 v[80:95], v[112:115], v[144:147], v[80:95]
	ds_read_b128 v[112:115], v197 offset:26624
	v_exp_f32_e32 v63, v63
	v_add_f32_e32 v239, v61, v239
	v_cvt_pk_bf16_f32 v56, v56, v57
	v_add_f32_e32 v238, v62, v238
	v_mfma_f32_32x32x16_bf16 v[64:79], v[116:119], v[144:147], v[64:79]
	ds_read_b128 v[116:119], v197 offset:31232
	v_cvt_pk_bf16_f32 v57, v58, v59
	v_add_f32_e32 v239, v63, v239
	v_cvt_pk_bf16_f32 v58, v60, v61
	v_cvt_pk_bf16_f32 v59, v62, v63
	s_waitcnt lgkmcnt(6)
	v_mfma_f32_32x32x16_bf16 v[80:95], v[120:123], v[148:151], v[80:95]
	ds_read_b128 v[120:123], v197 offset:26656
	v_exp_f32_e32 v32, v32
	v_exp_f32_e32 v33, v33
	v_exp_f32_e32 v34, v34
	v_add_f32_e32 v238, v32, v238
	v_mfma_f32_32x32x16_bf16 v[64:79], v[124:127], v[148:151], v[64:79]
	ds_read_b128 v[124:127], v197 offset:31264
	v_exp_f32_e32 v35, v35
	v_add_f32_e32 v239, v33, v239
	v_exp_f32_e32 v36, v36
	v_add_f32_e32 v238, v34, v238
	s_waitcnt lgkmcnt(6)
	v_mfma_f32_32x32x16_bf16 v[80:95], v[96:99], v[152:155], v[80:95]
	ds_read_b128 v[96:99], v197 offset:26688
	v_exp_f32_e32 v37, v37
	v_add_f32_e32 v239, v35, v239
	v_exp_f32_e32 v38, v38
	v_add_f32_e32 v238, v36, v238
	v_mfma_f32_32x32x16_bf16 v[64:79], v[100:103], v[152:155], v[64:79]
	ds_read_b128 v[100:103], v197 offset:31296
	v_exp_f32_e32 v39, v39
	v_add_f32_e32 v239, v37, v239
	v_cvt_pk_bf16_f32 v32, v32, v33
	v_add_f32_e32 v238, v38, v238
	s_waitcnt lgkmcnt(6)
	v_mfma_f32_32x32x16_bf16 v[80:95], v[104:107], v[156:159], v[80:95]
	ds_read_b128 v[104:107], v197 offset:26720
	v_cvt_pk_bf16_f32 v33, v34, v35
	v_add_f32_e32 v239, v39, v239
	v_cvt_pk_bf16_f32 v34, v36, v37
	v_cvt_pk_bf16_f32 v35, v38, v39
	v_mfma_f32_32x32x16_bf16 v[64:79], v[108:111], v[156:159], v[64:79]
	ds_read_b128 v[108:111], v197 offset:31328
	v_exp_f32_e32 v40, v40
	v_exp_f32_e32 v41, v41
	v_exp_f32_e32 v42, v42
	v_add_f32_e32 v238, v40, v238
	v_mfma_f32_32x32x16_bf16 v[80:95], v[132:135], v[180:183], v[80:95]
	v_exp_f32_e32 v43, v43
	v_add_f32_e32 v239, v41, v239
	v_exp_f32_e32 v44, v44
	v_add_f32_e32 v238, v42, v238
	v_mfma_f32_32x32x16_bf16 v[64:79], v[132:135], v[180:183], v[64:79]
	v_exp_f32_e32 v45, v45
	v_add_f32_e32 v239, v43, v239
	v_exp_f32_e32 v46, v46
	v_add_f32_e32 v238, v44, v238
	s_waitcnt lgkmcnt(4)
	v_mfma_f32_32x32x16_bf16 v[16:31], v[112:115], v[48:51], v[16:31]
	v_exp_f32_e32 v47, v47
	v_add_f32_e32 v239, v45, v239
	v_cvt_pk_bf16_f32 v40, v40, v41
	v_mfma_f32_32x32x16_bf16 v[0:15], v[116:119], v[48:51], v[0:15]
	v_add_f32_e32 v238, v46, v238
	v_cvt_pk_bf16_f32 v41, v42, v43
	v_add_f32_e32 v239, v47, v239
	v_mfma_f32_32x32x16_bf16 v[16:31], v[120:123], v[56:59], v[16:31]
	v_cvt_pk_bf16_f32 v42, v44, v45
	v_cvt_pk_bf16_f32 v43, v46, v47
	v_max3_f32 v112, v80, v64, v81
	v_mfma_f32_32x32x16_bf16 v[0:15], v[124:127], v[56:59], v[0:15]
	v_max3_f32 v113, v65, v82, v66
	v_max3_f32 v112, v83, v67, v112
	v_max3_f32 v113, v84, v68, v113
	s_waitcnt lgkmcnt(0)
	v_mfma_f32_32x32x16_bf16 v[16:31], v[96:99], v[32:35], v[16:31]
	v_max3_f32 v112, v85, v69, v112
	v_max3_f32 v113, v86, v70, v113
	v_max3_f32 v112, v87, v71, v112
	v_mfma_f32_32x32x16_bf16 v[0:15], v[100:103], v[32:35], v[0:15]
	v_max3_f32 v113, v88, v72, v113
	v_max3_f32 v112, v89, v73, v112
	v_max3_f32 v113, v90, v74, v113
	v_mfma_f32_32x32x16_bf16 v[16:31], v[104:107], v[40:43], v[16:31]
	v_max3_f32 v112, v91, v75, v112
	v_max3_f32 v113, v92, v76, v113
	v_max3_f32 v112, v93, v77, v112
	v_mfma_f32_32x32x16_bf16 v[0:15], v[108:111], v[40:43], v[0:15]
	v_max3_f32 v113, v94, v78, v113
	v_max3_f32 v112, v95, v79, v112
	v_max_f32_e32 v112, v112, v113
	s_waitcnt vmcnt(0)
	ds_write_b128 v250, v[160:163]
	ds_write_b128 v251, v[164:167]
	ds_write_b128 v252, v[168:171]
	ds_write_b128 v194, v[172:175] offset:35840
	ds_write_b128 v196, v[176:179] offset:35840
	v_cmp_lt_f32_e32 vcc, s65, v112
	s_cbranch_vccnz .Lm_rareB

; #define MFMA(a, b, c) __builtin_amdgcn_mfma_f32_32x32x16_bf16((a), (b), (c), 0, 0, 0)
; DI unsigned pack2(float a, float b) { f32x2v f = {a, b}; bf16x2v v = __builtin_convertvector(f, bf16x2v); return __builtin_bit_cast(unsigned, v); }
; DI float xhalf(float v) { return __shfl_xor(v, 32); }
;   template <int PAR>
;   DI void step(int t, f32x16 (&cur)[2], f32x16 (&nxt)[2]) {
;     if (t + 1 < nt) sstore_k(PAR ^ 1);
;     if (t > 0) sstore_v(PAR);
;     __syncthreads();
;     if (t + 1 < nt) qk(PAR ^ 1, nxt);
;     float mx = fmaxf(cur[0][0], cur[1][0]);
; #pragma unroll
;     for (int i = 1; i < 16; ++i) mx = fmaxf(fmaxf(cur[0][i], cur[1][i]), mx);
;     if (__builtin_amdgcn_ballot_w64(mx > ATT_THR) != 0ull) {
;       asm volatile("" ::: "memory");
;       mx = fmaxf(mx, xhalf(mx));
;       const float want = mref + fmaxf(mx, 0.f);
;       const float mn = __uint_as_float(pack2(want, 0.f) << 16);
;       const float d = mn - mref;
;       const float alpha = __builtin_amdgcn_exp2f(-d);
;       mref = mn;
;       l *= alpha;
; #pragma unroll
;       for (int a = 0; a < 2; ++a)
; #pragma unroll
;         for (int i = 0; i < 16; ++i) { o[a][i] *= alpha; cur[a][i] -= d; nxt[a][i] -= d; }
;       u32x4 q4 = {h == 0 ? (pack2(-mn, 0.f) & 0xffffu) : 0u, 0u, 0u, 0u};
;       qm = __builtin_bit_cast(bf16x8, q4);
;     }
;     float psum = 0.f;
; #pragma unroll
;     for (int kb2 = 0; kb2 < 2; ++kb2)
; #pragma unroll
;       for (int i = 0; i < 16; ++i) { const float pv = __builtin_amdgcn_exp2f(cur[kb2][i]); cur[kb2][i] = pv; psum += pv; }
;     l += psum;
;     if (t + 2 < nt) gload_k(t + 2);
;     if (t + 1 < nt) gload_v(t + 1);
;     const u16* vb = sV + PAR * VBUF + r * GP + h * 8;
; #pragma unroll
;     for (int kb2 = 0; kb2 < 2; ++kb2)
; #pragma unroll
;       for (int s2 = 0; s2 < 2; ++s2) {
;         u32x4 pk = {pack2(cur[kb2][8 * s2], cur[kb2][8 * s2 + 1]), pack2(cur[kb2][8 * s2 + 2], cur[kb2][8 * s2 + 3]),
;                     pack2(cur[kb2][8 * s2 + 4], cur[kb2][8 * s2 + 5]), pack2(cur[kb2][8 * s2 + 6], cur[kb2][8 * s2 + 7])};
;         const bf16x8 pf = __builtin_bit_cast(bf16x8, pk);
; #pragma unroll
;         for (int db = 0; db < 2; ++db) {
;           const bf16x8 a = *(const bf16x8*)(vb + db * 32 * GP + kb2 * 32 + s2 * 16);
;           o[db] = MFMA(a, pf, o[db]);
;         }
;       }
;   }
.Lm_skipVB:
	v_exp_f32_e32 v80, v80
	v_exp_f32_e32 v81, v81
	v_exp_f32_e32 v82, v82
	v_add_f32_e32 v238, v80, v238
	v_exp_f32_e32 v83, v83
	v_add_f32_e32 v239, v81, v239
	v_exp_f32_e32 v84, v84
	v_add_f32_e32 v238, v82, v238
	v_exp_f32_e32 v85, v85
	v_add_f32_e32 v239, v83, v239
	s_waitcnt lgkmcnt(0)
	s_barrier
	ds_read_b128 v[96:99], v236
	ds_read_b128 v[100:103], v236 offset:6656
	ds_read_b128 v[104:107], v236 offset:32
	ds_read_b128 v[108:111], v236 offset:6688
	ds_read_b128 v[112:115], v236 offset:64
	ds_read_b128 v[116:119], v236 offset:6720
	ds_read_b128 v[120:123], v236 offset:96
	ds_read_b128 v[124:127], v236 offset:6752
	v_exp_f32_e32 v86, v86
	v_add_f32_e32 v238, v84, v238
	v_exp_f32_e32 v87, v87
	v_add_f32_e32 v239, v85, v239
	v_cvt_pk_bf16_f32 v80, v80, v81
	v_add_f32_e32 v238, v86, v238
	s_waitcnt lgkmcnt(6)
	v_mfma_f32_32x32x16_bf16 v[48:63], v[96:99], v[136:139], 0
	ds_read_b128 v[96:99], v236 offset:128
	v_cvt_pk_bf16_f32 v81, v82, v83
	v_add_f32_e32 v239, v87, v239
	v_cvt_pk_bf16_f32 v82, v84, v85
	v_cvt_pk_bf16_f32 v83, v86, v87
	v_mfma_f32_32x32x16_bf16 v[32:47], v[100:103], v[136:139], 0
	ds_read_b128 v[100:103], v236 offset:6784
	v_exp_f32_e32 v88, v88
	v_exp_f32_e32 v89, v89
	v_exp_f32_e32 v90, v90
	v_add_f32_e32 v238, v88, v238
	s_waitcnt lgkmcnt(6)
	v_mfma_f32_32x32x16_bf16 v[48:63], v[104:107], v[140:143], v[48:63]
	ds_read_b128 v[104:107], v236 offset:160
	v_exp_f32_e32 v91, v91
	v_add_f32_e32 v239, v89, v239
	v_exp_f32_e32 v92, v92
	v_add_f32_e32 v238, v90, v238
	v_mfma_f32_32x32x16_bf16 v[32:47], v[108:111], v[140:143], v[32:47]
	ds_read_b128 v[108:111], v236 offset:6816
	v_exp_f32_e32 v93, v93
	v_add_f32_e32 v239, v91, v239
	v_exp_f32_e32 v94, v94
	v_add_f32_e32 v238, v92, v238
	s_waitcnt lgkmcnt(6)
	v_mfma_f32_32x32x16_bf16 v[48:63], v[112:115], v[144:147], v[48:63]
	ds_read_b128 v[112:115], v197 offset:35840
	v_exp_f32_e32 v95, v95
	v_add_f32_e32 v239, v93, v239
	v_cvt_pk_bf16_f32 v88, v88, v89
	v_add_f32_e32 v238, v94, v238
	v_mfma_f32_32x32x16_bf16 v[32:47], v[116:119], v[144:147], v[32:47]
	ds_read_b128 v[116:119], v197 offset:40448
	v_cvt_pk_bf16_f32 v89, v90, v91
	v_add_f32_e32 v239, v95, v239
	v_cvt_pk_bf16_f32 v90, v92, v93
	v_cvt_pk_bf16_f32 v91, v94, v95
	s_waitcnt lgkmcnt(6)
	v_mfma_f32_32x32x16_bf16 v[48:63], v[120:123], v[148:151], v[48:63]
	ds_read_b128 v[120:123], v197 offset:35872
	v_exp_f32_e32 v64, v64
	v_exp_f32_e32 v65, v65
	v_exp_f32_e32 v66, v66
	v_add_f32_e32 v238, v64, v238
	v_mfma_f32_32x32x16_bf16 v[32:47], v[124:127], v[148:151], v[32:47]
	ds_read_b128 v[124:127], v197 offset:40480
	v_exp_f32_e32 v67, v67
	v_add_f32_e32 v239, v65, v239
	v_exp_f32_e32 v68, v68
	v_add_f32_e32 v238, v66, v238
	s_waitcnt lgkmcnt(6)
	v_mfma_f32_32x32x16_bf16 v[48:63], v[96:99], v[152:155], v[48:63]
	ds_read_b128 v[96:99], v197 offset:35904
	v_exp_f32_e32 v69, v69
	v_add_f32_e32 v239, v67, v239
	v_exp_f32_e32 v70, v70
	v_add_f32_e32 v238, v68, v238
	v_mfma_f32_32x32x16_bf16 v[32:47], v[100:103], v[152:155], v[32:47]
	ds_read_b128 v[100:103], v197 offset:40512
	v_exp_f32_e32 v71, v71
	v_add_f32_e32 v239, v69, v239
	v_cvt_pk_bf16_f32 v64, v64, v65
	v_add_f32_e32 v238, v70, v238
	s_waitcnt lgkmcnt(6)
	v_mfma_f32_32x32x16_bf16 v[48:63], v[104:107], v[156:159], v[48:63]
	ds_read_b128 v[104:107], v197 offset:35936
	v_cvt_pk_bf16_f32 v65, v66, v67
	v_add_f32_e32 v239, v71, v239
	v_cvt_pk_bf16_f32 v66, v68, v69
	v_cvt_pk_bf16_f32 v67, v70, v71
	v_mfma_f32_32x32x16_bf16 v[32:47], v[108:111], v[156:159], v[32:47]
	ds_read_b128 v[108:111], v197 offset:40544
	v_exp_f32_e32 v72, v72
	v_exp_f32_e32 v73, v73
	v_exp_f32_e32 v74, v74
	v_add_f32_e32 v238, v72, v238
	v_mfma_f32_32x32x16_bf16 v[48:63], v[132:135], v[180:183], v[48:63]
	v_exp_f32_e32 v75, v75
	v_add_f32_e32 v239, v73, v239
	v_exp_f32_e32 v76, v76
	v_add_f32_e32 v238, v74, v238
	v_mfma_f32_32x32x16_bf16 v[32:47], v[132:135], v[180:183], v[32:47]
	v_exp_f32_e32 v77, v77
	v_add_f32_e32 v239, v75, v239
	v_exp_f32_e32 v78, v78
	v_add_f32_e32 v238, v76, v238
	s_waitcnt lgkmcnt(4)
	v_mfma_f32_32x32x16_bf16 v[16:31], v[112:115], v[80:83], v[16:31]
	v_exp_f32_e32 v79, v79
	v_add_f32_e32 v239, v77, v239
	v_cvt_pk_bf16_f32 v72, v72, v73
	v_mfma_f32_32x32x16_bf16 v[0:15], v[116:119], v[80:83], v[0:15]
	v_add_f32_e32 v238, v78, v238
	v_cvt_pk_bf16_f32 v73, v74, v75
	v_add_f32_e32 v239, v79, v239
	v_mfma_f32_32x32x16_bf16 v[16:31], v[120:123], v[88:91], v[16:31]
	v_cvt_pk_bf16_f32 v74, v76, v77
	v_cvt_pk_bf16_f32 v75, v78, v79
	v_max3_f32 v112, v48, v32, v49
	v_mfma_f32_32x32x16_bf16 v[0:15], v[124:127], v[88:91], v[0:15]
	v_max3_f32 v113, v33, v50, v34
	v_max3_f32 v112, v51, v35, v112
	v_max3_f32 v113, v52, v36, v113
	s_waitcnt lgkmcnt(0)
	v_mfma_f32_32x32x16_bf16 v[16:31], v[96:99], v[64:67], v[16:31]
	v_max3_f32 v112, v53, v37, v112
	v_max3_f32 v113, v54, v38, v113
	v_max3_f32 v112, v55, v39, v112
	v_mfma_f32_32x32x16_bf16 v[0:15], v[100:103], v[64:67], v[0:15]
	v_max3_f32 v113, v56, v40, v113
	v_max3_f32 v112, v57, v41, v112
	v_max3_f32 v113, v58, v42, v113
	v_mfma_f32_32x32x16_bf16 v[16:31], v[104:107], v[72:75], v[16:31]
	v_max3_f32 v112, v59, v43, v112
	v_max3_f32 v113, v60, v44, v113
	v_max3_f32 v112, v61, v45, v112
	v_mfma_f32_32x32x16_bf16 v[0:15], v[108:111], v[72:75], v[0:15]
	v_max3_f32 v113, v62, v46, v113
	v_max3_f32 v112, v63, v47, v112
	v_max_f32_e32 v112, v112, v113
	v_lshl_add_u64 v[130:131], v[130:131], 0, s[84:85]
	v_lshl_add_u64 v[220:221], v[220:221], 0, s[84:85]
	s_mov_b32 s0, s31
	s_add_i32 s31, s31, 2
	s_cmp_lt_u32 s0, s19
	s_cbranch_scc1 .LBB0_268
	s_branch .Lm_fold
.Lm_fold:
	v_add_f32_e32 v237, v237, v238
	v_add_f32_e32 v237, v237, v239
	s_branch .LBB0_283
; DI unsigned pack2(float a, float b) { f32x2v f = {a, b}; bf16x2v v = __builtin_convertvector(f, bf16x2v); return __builtin_bit_cast(unsigned, v); }
; DI float xhalf(float v) { return __shfl_xor(v, 32); }
;   template <int PAR>
;   DI void step(int t, f32x16 (&cur)[2], f32x16 (&nxt)[2]) {
;     ...
;     if (__builtin_amdgcn_ballot_w64(mx > ATT_THR) != 0ull) {
;       asm volatile("" ::: "memory");
;       mx = fmaxf(mx, xhalf(mx));
;       const float want = mref + fmaxf(mx, 0.f);
;       const float mn = __uint_as_float(pack2(want, 0.f) << 16);
;       const float d = mn - mref;
;       const float alpha = __builtin_amdgcn_exp2f(-d);
;       mref = mn;
;       l *= alpha;
; #pragma unroll
;       for (int a = 0; a < 2; ++a)
; #pragma unroll
;         for (int i = 0; i < 16; ++i) { o[a][i] *= alpha; cur[a][i] -= d; nxt[a][i] -= d; }
;       u32x4 q4 = {h == 0 ? (pack2(-mn, 0.f) & 0xffffu) : 0u, 0u, 0u, 0u};
;       qm = __builtin_bit_cast(bf16x8, q4);
;     }
.Lmf_rareA:
	v_cmp_lt_i32_e64 s[0:1], v229, v228
	s_nop 1
	v_cndmask_b32_e64 v113, v227, v229, s[0:1]
	v_lshlrev_b32_e32 v113, 2, v113
	ds_bpermute_b32 v113, v113, v112
	s_waitcnt lgkmcnt(0)
	v_max3_f32 v112, v112, v113, 0
	v_add_f32_e32 v112, v218, v112
	v_cvt_pk_bf16_f32 v112, v112, 0
	v_lshlrev_b32_e32 v113, 16, v112
	v_sub_f32_e32 v112, v113, v218
	v_exp_f32_e64 v114, -v112
	v_pk_add_f32 v[48:49], v[48:49], v[112:113] op_sel_hi:[1,0] neg_lo:[0,1] neg_hi:[0,1]
	v_pk_add_f32 v[50:51], v[50:51], v[112:113] op_sel_hi:[1,0] neg_lo:[0,1] neg_hi:[0,1]
	v_pk_add_f32 v[52:53], v[52:53], v[112:113] op_sel_hi:[1,0] neg_lo:[0,1] neg_hi:[0,1]
	v_pk_add_f32 v[54:55], v[54:55], v[112:113] op_sel_hi:[1,0] neg_lo:[0,1] neg_hi:[0,1]
	v_pk_add_f32 v[56:57], v[56:57], v[112:113] op_sel_hi:[1,0] neg_lo:[0,1] neg_hi:[0,1]
	v_pk_add_f32 v[58:59], v[58:59], v[112:113] op_sel_hi:[1,0] neg_lo:[0,1] neg_hi:[0,1]
	v_pk_add_f32 v[60:61], v[60:61], v[112:113] op_sel_hi:[1,0] neg_lo:[0,1] neg_hi:[0,1]
	v_pk_add_f32 v[62:63], v[62:63], v[112:113] op_sel_hi:[1,0] neg_lo:[0,1] neg_hi:[0,1]
	v_pk_add_f32 v[32:33], v[32:33], v[112:113] op_sel_hi:[1,0] neg_lo:[0,1] neg_hi:[0,1]
	v_pk_add_f32 v[34:35], v[34:35], v[112:113] op_sel_hi:[1,0] neg_lo:[0,1] neg_hi:[0,1]
	v_pk_add_f32 v[36:37], v[36:37], v[112:113] op_sel_hi:[1,0] neg_lo:[0,1] neg_hi:[0,1]
	v_pk_add_f32 v[38:39], v[38:39], v[112:113] op_sel_hi:[1,0] neg_lo:[0,1] neg_hi:[0,1]
	v_pk_add_f32 v[40:41], v[40:41], v[112:113] op_sel_hi:[1,0] neg_lo:[0,1] neg_hi:[0,1]
	v_pk_add_f32 v[42:43], v[42:43], v[112:113] op_sel_hi:[1,0] neg_lo:[0,1] neg_hi:[0,1]
	v_pk_add_f32 v[44:45], v[44:45], v[112:113] op_sel_hi:[1,0] neg_lo:[0,1] neg_hi:[0,1]
	v_pk_add_f32 v[46:47], v[46:47], v[112:113] op_sel_hi:[1,0] neg_lo:[0,1] neg_hi:[0,1]
	v_xor_b32_e32 v112, 0x80000000, v113
	v_cvt_pk_bf16_f32 v112, v112, 0
	v_and_b32_e32 v112, 0xffff, v112
	v_mul_f32_e32 v237, v237, v114
	v_pk_mul_f32 v[238:239], v[238:239], v[114:115] op_sel_hi:[1,0]
	v_pk_mul_f32 v[30:31], v[30:31], v[114:115] op_sel_hi:[1,0]
	v_pk_mul_f32 v[28:29], v[28:29], v[114:115] op_sel_hi:[1,0]
	v_pk_mul_f32 v[26:27], v[26:27], v[114:115] op_sel_hi:[1,0]
	v_pk_mul_f32 v[24:25], v[24:25], v[114:115] op_sel_hi:[1,0]
	v_pk_mul_f32 v[22:23], v[22:23], v[114:115] op_sel_hi:[1,0]
	v_pk_mul_f32 v[20:21], v[20:21], v[114:115] op_sel_hi:[1,0]
	v_pk_mul_f32 v[18:19], v[18:19], v[114:115] op_sel_hi:[1,0]
	v_pk_mul_f32 v[16:17], v[16:17], v[114:115] op_sel_hi:[1,0]
	v_pk_mul_f32 v[14:15], v[14:15], v[114:115] op_sel_hi:[1,0]
	v_pk_mul_f32 v[12:13], v[12:13], v[114:115] op_sel_hi:[1,0]
	v_pk_mul_f32 v[10:11], v[10:11], v[114:115] op_sel_hi:[1,0]
	v_pk_mul_f32 v[8:9], v[8:9], v[114:115] op_sel_hi:[1,0]
	v_pk_mul_f32 v[6:7], v[6:7], v[114:115] op_sel_hi:[1,0]
	v_pk_mul_f32 v[4:5], v[4:5], v[114:115] op_sel_hi:[1,0]
	v_pk_mul_f32 v[2:3], v[2:3], v[114:115] op_sel_hi:[1,0]
	v_pk_mul_f32 v[0:1], v[0:1], v[114:115] op_sel_hi:[1,0]
	v_cndmask_b32_e64 v180, 0, v112, s[6:7]
	v_mov_b32_e32 v218, v113
	s_branch .Lm_rareA_ret
.Lmf_rareB:
	v_cmp_lt_i32_e64 s[0:1], v229, v228
	s_nop 1
	v_cndmask_b32_e64 v113, v227, v229, s[0:1]
	v_lshlrev_b32_e32 v113, 2, v113
	ds_bpermute_b32 v113, v113, v112
	s_waitcnt lgkmcnt(0)
	v_max3_f32 v112, v112, v113, 0
	v_add_f32_e32 v112, v218, v112
	v_cvt_pk_bf16_f32 v112, v112, 0
	v_lshlrev_b32_e32 v113, 16, v112
	v_sub_f32_e32 v112, v113, v218
	v_exp_f32_e64 v114, -v112
	v_pk_add_f32 v[80:81], v[80:81], v[112:113] op_sel_hi:[1,0] neg_lo:[0,1] neg_hi:[0,1]
	v_pk_add_f32 v[82:83], v[82:83], v[112:113] op_sel_hi:[1,0] neg_lo:[0,1] neg_hi:[0,1]
	v_pk_add_f32 v[84:85], v[84:85], v[112:113] op_sel_hi:[1,0] neg_lo:[0,1] neg_hi:[0,1]
	v_pk_add_f32 v[86:87], v[86:87], v[112:113] op_sel_hi:[1,0] neg_lo:[0,1] neg_hi:[0,1]
	v_pk_add_f32 v[88:89], v[88:89], v[112:113] op_sel_hi:[1,0] neg_lo:[0,1] neg_hi:[0,1]
	v_pk_add_f32 v[90:91], v[90:91], v[112:113] op_sel_hi:[1,0] neg_lo:[0,1] neg_hi:[0,1]
	v_pk_add_f32 v[92:93], v[92:93], v[112:113] op_sel_hi:[1,0] neg_lo:[0,1] neg_hi:[0,1]
	v_pk_add_f32 v[94:95], v[94:95], v[112:113] op_sel_hi:[1,0] neg_lo:[0,1] neg_hi:[0,1]
	v_pk_add_f32 v[64:65], v[64:65], v[112:113] op_sel_hi:[1,0] neg_lo:[0,1] neg_hi:[0,1]
	v_pk_add_f32 v[66:67], v[66:67], v[112:113] op_sel_hi:[1,0] neg_lo:[0,1] neg_hi:[0,1]
	v_pk_add_f32 v[68:69], v[68:69], v[112:113] op_sel_hi:[1,0] neg_lo:[0,1] neg_hi:[0,1]
	v_pk_add_f32 v[70:71], v[70:71], v[112:113] op_sel_hi:[1,0] neg_lo:[0,1] neg_hi:[0,1]
	v_pk_add_f32 v[72:73], v[72:73], v[112:113] op_sel_hi:[1,0] neg_lo:[0,1] neg_hi:[0,1]
	v_pk_add_f32 v[74:75], v[74:75], v[112:113] op_sel_hi:[1,0] neg_lo:[0,1] neg_hi:[0,1]
	v_pk_add_f32 v[76:77], v[76:77], v[112:113] op_sel_hi:[1,0] neg_lo:[0,1] neg_hi:[0,1]
	v_pk_add_f32 v[78:79], v[78:79], v[112:113] op_sel_hi:[1,0] neg_lo:[0,1] neg_hi:[0,1]
	v_xor_b32_e32 v112, 0x80000000, v113
	v_cvt_pk_bf16_f32 v112, v112, 0
	v_and_b32_e32 v112, 0xffff, v112
	v_mul_f32_e32 v237, v237, v114
	v_pk_mul_f32 v[238:239], v[238:239], v[114:115] op_sel_hi:[1,0]
	v_pk_mul_f32 v[30:31], v[30:31], v[114:115] op_sel_hi:[1,0]
	v_pk_mul_f32 v[28:29], v[28:29], v[114:115] op_sel_hi:[1,0]
	v_pk_mul_f32 v[26:27], v[26:27], v[114:115] op_sel_hi:[1,0]
	v_pk_mul_f32 v[24:25], v[24:25], v[114:115] op_sel_hi:[1,0]
	v_pk_mul_f32 v[22:23], v[22:23], v[114:115] op_sel_hi:[1,0]
	v_pk_mul_f32 v[20:21], v[20:21], v[114:115] op_sel_hi:[1,0]
	v_pk_mul_f32 v[18:19], v[18:19], v[114:115] op_sel_hi:[1,0]
	v_pk_mul_f32 v[16:17], v[16:17], v[114:115] op_sel_hi:[1,0]
	v_pk_mul_f32 v[14:15], v[14:15], v[114:115] op_sel_hi:[1,0]
	v_pk_mul_f32 v[12:13], v[12:13], v[114:115] op_sel_hi:[1,0]
	v_pk_mul_f32 v[10:11], v[10:11], v[114:115] op_sel_hi:[1,0]
	v_pk_mul_f32 v[8:9], v[8:9], v[114:115] op_sel_hi:[1,0]
	v_pk_mul_f32 v[6:7], v[6:7], v[114:115] op_sel_hi:[1,0]
	v_pk_mul_f32 v[4:5], v[4:5], v[114:115] op_sel_hi:[1,0]
	v_pk_mul_f32 v[2:3], v[2:3], v[114:115] op_sel_hi:[1,0]
	v_pk_mul_f32 v[0:1], v[0:1], v[114:115] op_sel_hi:[1,0]
	v_cndmask_b32_e64 v180, 0, v112, s[6:7]
	v_mov_b32_e32 v218, v113
	s_branch .Lm_rareB_ret
